# GEMM units: first K-loop iteration peeled, each accumulator's first MFMA takes C=0 (inline), accumulator zero-init removed (six live instances); stacked on stack24
# speedup vs baseline: 1.0110x; 1.0110x over previous
; #define PG8_STAGE(bufoff, gbase, voff) do { _Pragma("unroll") for (int _i = 0; _i < 2; ++_i) \
;         __builtin_amdgcn_global_load_lds((const unsigned*)((const char*)(gbase) + (voff)[_i]), (PG8_LAS unsigned*)(lds + (bufoff) + ldsw + _i * 8192), 16, 0, 0); } while (0)
; #define PG8_LDA(dst, b, h) do { _Pragma("unroll") for (int m = 0; m < 4; ++m) _Pragma("unroll") for (int k = 0; k < 2; ++k) dst[m][k] = *(const PG8_LAS bf16x8*)(lds + PG8_SA(b, h) + aoff + m * 2048 + k * 1024); } while (0)
; #define PG8_LDB(dst, b, h) do { _Pragma("unroll") for (int n = 0; n < 2; ++n) _Pragma("unroll") for (int k = 0; k < 2; ++k) dst[n][k] = *(const PG8_LAS bf16x8*)(lds + PG8_SB(b, h) + boff + n * 2048 + k * 1024); } while (0)
; #define PG8_WAIT_V(n) asm volatile("s_waitcnt vmcnt(" #n ")" ::: "memory")
; #define PG8_WAIT_L(n) asm volatile("s_waitcnt lgkmcnt(" #n ")" ::: "memory")
; #define PG8_BAR __builtin_amdgcn_s_barrier()
; #define PG8_SCHED __builtin_amdgcn_sched_barrier(0)
; template <class Epi, class Sched, bool ALIGN_EPI = false, bool SP2 = false>
; __device__ __forceinline__ void gemm_phase(PG8_LAS unsigned char* lds, const Gemm g, const Sched& S, const Epi& E) {
;     ...
;         const bool has_next = S.next(ui + 1, nxt);
;         const char* nA = has_next ? (const char*)g.A + (size_t)nxt.pm * tstep : cA; const char* nB = has_next ? (const char*)g.Bt + (size_t)nxt.pn * tstep : cB;
;         for (int t = 0; t < nt; t += 2) {
;             const bool last = (t == nt - 2);
;             const char* a1 = cA + (size_t)(t + 1) * kstep;
;             const char* a2 = last ? nA : cA + (size_t)(t + 2) * kstep; const char* b2 = last ? nB : cB + (size_t)(t + 2) * kstep;
;             const char* a3 = a2 + kstep; const char* b3 = b2 + kstep;
;             if (last && has_next) S.a_ready(nxt);
;             if constexpr (SP2) {
;             PG8_LDB(B0, 0, 0); PG8_LDB(B1, 0, 1); PG8_SCHED; PG8_LDA(At, 0, 0); PG8_STAGE(PG8_SA(1, 1), a1 + hstep, voffA);
;             PG8_WAIT_V(8); PG8_WAIT_L(0); PG8_BAR; PG8_MMA(0, 0, At, B0); PG8_MMA(0, 1, At, B1); PG8_BAR; PG8_SCHED;
;             PG8_LDA(At, 0, 1); PG8_STAGE(PG8_SB(0, 0), b2, voffB); PG8_STAGE(PG8_SB(0, 1), b2 + hstep, voffB); PG8_STAGE(PG8_SA(0, 0), a2, voffA);
;             PG8_WAIT_V(8); PG8_WAIT_L(0); PG8_BAR; PG8_MMA(1, 0, At, B0); PG8_MMA(1, 1, At, B1); PG8_BAR; PG8_SCHED;
.LBB0_163:
	s_ashr_i32 s51, s50, 31
	s_lshl_b64 s[36:37], s[50:51], 19
	s_add_u32 s62, s2, s36
	s_addc_u32 s63, s14, s37
	s_and_b64 s[36:37], s[40:41], exec
	s_cselect_b32 s36, s63, s65
	s_cselect_b32 s37, s62, s64
	s_ashr_i32 s53, s52, 31
	s_lshl_b64 s[66:67], s[52:53], 19
	s_add_u32 s66, s15, s66
	s_addc_u32 s67, s16, s67
	s_and_b64 s[72:73], s[40:41], exec
	s_cselect_b32 s51, s67, s59
	s_cselect_b32 s53, s66, s58
	s_add_u32 s72, s64, 0x40080
	s_addc_u32 s73, s65, 0
	s_add_u32 s92, s58, 0x100
	s_addc_u32 s93, s59, 0
	s_mov_b32 s94, -2
	s_and_b64 s[98:99], exec, s[48:49]
	s_cbranch_scc1 .Lsp_1
	s_setprio 1
.Lsp_1:
	s_add_u32 s58, s72, 0xfffc0080
	s_addc_u32 s59, s73, -1
	s_add_i32 s84, 0, 0x10000
	s_cmp_eq_u32 s94, 12
	s_cselect_b32 s65, s36, s59
	s_cselect_b32 s64, s37, s58
	v_add_u32_e32 v140, s84, v146
	s_cselect_b32 s59, s51, s93
	s_cselect_b32 s58, s53, s92
	s_add_i32 s96, 0, 0x14000
	ds_read_b128 v[142:145], v140
	ds_read_b128 v[150:153], v140 offset:1024
	ds_read_b128 v[154:157], v140 offset:2048
	ds_read_b128 v[158:161], v140 offset:3072
	v_add_u32_e32 v140, s96, v146
	ds_read_b128 v[162:165], v140
	ds_read_b128 v[166:169], v140 offset:1024
	ds_read_b128 v[170:173], v140 offset:2048
	ds_read_b128 v[174:177], v140 offset:3072
	v_lshl_add_u64 v[186:187], s[72:73], 0, v[136:137]
	s_add_i32 m0, s19, 0xc000
	ds_read_b128 v[178:181], v148
	ds_read_b128 v[182:185], v148 offset:1024
	ds_read_b128 v[190:193], v148 offset:2048
	ds_read_b128 v[194:197], v148 offset:3072
	ds_read_b128 v[198:201], v148 offset:4096
	ds_read_b128 v[202:205], v148 offset:5120
	ds_read_b128 v[206:209], v148 offset:6144
	ds_read_b128 v[228:231], v148 offset:7168
	global_load_lds_dwordx4 v[186:187], off
	v_lshl_add_u64 v[186:187], s[72:73], 0, v[138:139]
	s_add_i32 m0, s19, 0xe000
	s_nop 0
	global_load_lds_dwordx4 v[186:187], off
	s_waitcnt vmcnt(8)
	s_waitcnt lgkmcnt(0)
	s_barrier
	s_waitcnt lgkmcnt(0)
	v_mfma_f32_16x16x32_bf16 v[124:127], v[142:145], v[178:181], 0
	v_mfma_f32_16x16x32_bf16 v[120:123], v[154:157], v[178:181], 0
	v_mfma_f32_16x16x32_bf16 v[116:119], v[142:145], v[190:193], 0
	v_mfma_f32_16x16x32_bf16 v[112:115], v[154:157], v[190:193], 0
	v_mfma_f32_16x16x32_bf16 v[108:111], v[142:145], v[198:201], 0
	v_mfma_f32_16x16x32_bf16 v[104:107], v[154:157], v[198:201], 0
	v_mfma_f32_16x16x32_bf16 v[100:103], v[142:145], v[206:209], 0
	v_mfma_f32_16x16x32_bf16 v[96:99], v[154:157], v[206:209], 0
	v_mfma_f32_16x16x32_bf16 v[124:127], v[150:153], v[182:185], v[124:127]
	v_mfma_f32_16x16x32_bf16 v[120:123], v[158:161], v[182:185], v[120:123]
	v_mfma_f32_16x16x32_bf16 v[116:119], v[150:153], v[194:197], v[116:119]
	v_mfma_f32_16x16x32_bf16 v[112:115], v[158:161], v[194:197], v[112:115]
	v_mfma_f32_16x16x32_bf16 v[108:111], v[150:153], v[202:205], v[108:111]
	v_mfma_f32_16x16x32_bf16 v[104:107], v[158:161], v[202:205], v[104:107]
	v_mfma_f32_16x16x32_bf16 v[100:103], v[150:153], v[228:231], v[100:103]
	v_mfma_f32_16x16x32_bf16 v[96:99], v[158:161], v[228:231], v[96:99]
	v_mfma_f32_16x16x32_bf16 v[92:95], v[162:165], v[178:181], 0
	v_mfma_f32_16x16x32_bf16 v[88:91], v[170:173], v[178:181], 0
	v_mfma_f32_16x16x32_bf16 v[84:87], v[162:165], v[190:193], 0
	v_mfma_f32_16x16x32_bf16 v[80:83], v[170:173], v[190:193], 0
	v_mfma_f32_16x16x32_bf16 v[76:79], v[162:165], v[198:201], 0
	v_mfma_f32_16x16x32_bf16 v[72:75], v[170:173], v[198:201], 0
	v_mfma_f32_16x16x32_bf16 v[68:71], v[162:165], v[206:209], 0
	v_mfma_f32_16x16x32_bf16 v[64:67], v[170:173], v[206:209], 0
	v_mfma_f32_16x16x32_bf16 v[92:95], v[166:169], v[182:185], v[92:95]
	v_mfma_f32_16x16x32_bf16 v[88:91], v[174:177], v[182:185], v[88:91]
	v_mfma_f32_16x16x32_bf16 v[84:87], v[166:169], v[194:197], v[84:87]
	v_mfma_f32_16x16x32_bf16 v[80:83], v[174:177], v[194:197], v[80:83]
	v_mfma_f32_16x16x32_bf16 v[76:79], v[166:169], v[202:205], v[76:79]
	v_mfma_f32_16x16x32_bf16 v[72:75], v[174:177], v[202:205], v[72:75]
	v_mfma_f32_16x16x32_bf16 v[68:71], v[166:169], v[228:231], v[68:71]
	v_mfma_f32_16x16x32_bf16 v[64:67], v[174:177], v[228:231], v[64:67]
	s_barrier
	s_add_i32 s84, s84, s18
	v_lshl_add_u64 v[186:187], s[58:59], 0, v[128:129]
	s_mov_b32 m0, s84
	ds_read_b128 v[178:181], v148 offset:16384
	ds_read_b128 v[182:185], v148 offset:17408
	ds_read_b128 v[190:193], v148 offset:18432
	ds_read_b128 v[194:197], v148 offset:19456
	ds_read_b128 v[198:201], v148 offset:20480
	ds_read_b128 v[202:205], v148 offset:21504
	ds_read_b128 v[206:209], v148 offset:22528
	ds_read_b128 v[228:231], v148 offset:23552
	global_load_lds_dwordx4 v[186:187], off
	s_add_i32 m0, s84, 0x2000
	s_add_u32 s84, s58, 0x40000
	v_lshl_add_u64 v[188:189], s[58:59], 0, v[130:131]
	s_addc_u32 s85, s59, 0
	s_add_i32 s96, s96, s18
	global_load_lds_dwordx4 v[188:189], off
	v_lshl_add_u64 v[210:211], s[84:85], 0, v[128:129]
	s_mov_b32 m0, s96
	v_lshl_add_u64 v[232:233], s[64:65], 0, v[132:133]
	global_load_lds_dwordx4 v[210:211], off
	v_lshl_add_u64 v[210:211], s[84:85], 0, v[130:131]
	s_add_i32 m0, s96, 0x2000
	s_nop 0
	global_load_lds_dwordx4 v[210:211], off
	v_lshl_add_u64 v[210:211], s[64:65], 0, v[134:135]
	s_mov_b32 m0, s19
	s_nop 0
	global_load_lds_dwordx4 v[210:211], off
	s_mov_b32 m0, s20
	s_nop 0
	global_load_lds_dwordx4 v[232:233], off
	s_waitcnt vmcnt(8)
	s_waitcnt lgkmcnt(0)
	s_barrier
; #define PG8_STAGE(bufoff, gbase, voff) do { _Pragma("unroll") for (int _i = 0; _i < 2; ++_i) \
;         __builtin_amdgcn_global_load_lds((const unsigned*)((const char*)(gbase) + (voff)[_i]), (PG8_LAS unsigned*)(lds + (bufoff) + ldsw + _i * 8192), 16, 0, 0); } while (0)
; #define PG8_LDA(dst, b, h) do { _Pragma("unroll") for (int m = 0; m < 4; ++m) _Pragma("unroll") for (int k = 0; k < 2; ++k) dst[m][k] = *(const PG8_LAS bf16x8*)(lds + PG8_SA(b, h) + aoff + m * 2048 + k * 1024); } while (0)
; #define PG8_LDB(dst, b, h) do { _Pragma("unroll") for (int n = 0; n < 2; ++n) _Pragma("unroll") for (int k = 0; k < 2; ++k) dst[n][k] = *(const PG8_LAS bf16x8*)(lds + PG8_SB(b, h) + boff + n * 2048 + k * 1024); } while (0)
; #define PG8_MMA(ai, bj, At, Bt) do { __builtin_amdgcn_s_setprio(1); _Pragma("unroll") for (int m = 0; m < 4; ++m) _Pragma("unroll") for (int n = 0; n < 2; ++n) _Pragma("unroll") for (int k = 0; k < 2; ++k) \
;         acc[ai][bj][m][n] = __builtin_amdgcn_mfma_f32_16x16x32_bf16(Bt[n][k], At[m][k], acc[ai][bj][m][n], 0, 0, 0); __builtin_amdgcn_s_setprio(0); } while (0)
; #define PG8_WAIT_V(n) asm volatile("s_waitcnt vmcnt(" #n ")" ::: "memory")
; #define PG8_WAIT_L(n) asm volatile("s_waitcnt lgkmcnt(" #n ")" ::: "memory")
; #define PG8_BAR __builtin_amdgcn_s_barrier()
; #define PG8_SCHED __builtin_amdgcn_sched_barrier(0)
; template <class Epi, class Sched, bool ALIGN_EPI = false, bool SP2 = false>
; __device__ __forceinline__ void gemm_phase(PG8_LAS unsigned char* lds, const Gemm g, const Sched& S, const Epi& E) {
;     ...
;             PG8_WAIT_V(8); PG8_WAIT_L(0); PG8_BAR; PG8_MMA(1, 0, At, B0); PG8_MMA(1, 1, At, B1); PG8_BAR; PG8_SCHED;
;             PG8_LDB(B0, 1, 0); PG8_LDB(B1, 1, 1); PG8_SCHED; PG8_LDA(At, 1, 0); PG8_STAGE(PG8_SA(0, 1), a2 + hstep, voffA);
;             PG8_WAIT_V(8); PG8_WAIT_L(0); PG8_BAR; PG8_MMA(0, 0, At, B0); PG8_MMA(0, 1, At, B1); PG8_BAR; PG8_SCHED;
	s_waitcnt lgkmcnt(0)
	v_mfma_f32_16x16x32_bf16 v[60:63], v[142:145], v[178:181], 0
	v_mfma_f32_16x16x32_bf16 v[56:59], v[154:157], v[178:181], 0
	v_mfma_f32_16x16x32_bf16 v[52:55], v[142:145], v[190:193], 0
	v_mfma_f32_16x16x32_bf16 v[48:51], v[154:157], v[190:193], 0
	v_mfma_f32_16x16x32_bf16 v[44:47], v[142:145], v[198:201], 0
	v_mfma_f32_16x16x32_bf16 v[40:43], v[154:157], v[198:201], 0
	v_mfma_f32_16x16x32_bf16 v[36:39], v[142:145], v[206:209], 0
	v_mfma_f32_16x16x32_bf16 v[32:35], v[154:157], v[206:209], 0
	v_mfma_f32_16x16x32_bf16 v[60:63], v[150:153], v[182:185], v[60:63]
	v_mfma_f32_16x16x32_bf16 v[56:59], v[158:161], v[182:185], v[56:59]
	v_mfma_f32_16x16x32_bf16 v[52:55], v[150:153], v[194:197], v[52:55]
	v_mfma_f32_16x16x32_bf16 v[48:51], v[158:161], v[194:197], v[48:51]
	v_mfma_f32_16x16x32_bf16 v[44:47], v[150:153], v[202:205], v[44:47]
	v_mfma_f32_16x16x32_bf16 v[40:43], v[158:161], v[202:205], v[40:43]
	v_mfma_f32_16x16x32_bf16 v[36:39], v[150:153], v[228:231], v[36:39]
	v_mfma_f32_16x16x32_bf16 v[32:35], v[158:161], v[228:231], v[32:35]
	v_mfma_f32_16x16x32_bf16 v[28:31], v[162:165], v[178:181], 0
	v_mfma_f32_16x16x32_bf16 v[24:27], v[170:173], v[178:181], 0
	v_mfma_f32_16x16x32_bf16 v[20:23], v[162:165], v[190:193], 0
	v_mfma_f32_16x16x32_bf16 v[16:19], v[170:173], v[190:193], 0
	v_mfma_f32_16x16x32_bf16 v[12:15], v[162:165], v[198:201], 0
	v_mfma_f32_16x16x32_bf16 v[8:11], v[170:173], v[198:201], 0
	v_mfma_f32_16x16x32_bf16 v[4:7], v[162:165], v[206:209], 0
	v_mfma_f32_16x16x32_bf16 v[0:3], v[170:173], v[206:209], 0
	v_mfma_f32_16x16x32_bf16 v[28:31], v[166:169], v[182:185], v[28:31]
	v_mfma_f32_16x16x32_bf16 v[24:27], v[174:177], v[182:185], v[24:27]
	v_mfma_f32_16x16x32_bf16 v[20:23], v[166:169], v[194:197], v[20:23]
	v_mfma_f32_16x16x32_bf16 v[16:19], v[174:177], v[194:197], v[16:19]
	v_mfma_f32_16x16x32_bf16 v[12:15], v[166:169], v[202:205], v[12:15]
	v_mfma_f32_16x16x32_bf16 v[8:11], v[174:177], v[202:205], v[8:11]
	v_mfma_f32_16x16x32_bf16 v[4:7], v[166:169], v[228:231], v[4:7]
	v_mfma_f32_16x16x32_bf16 v[0:3], v[174:177], v[228:231], v[0:3]
	s_barrier
	s_add_i32 s84, 0, 0x18000
	v_add_u32_e32 v140, s84, v146
	s_add_i32 s85, 0, 0x1c000
	ds_read_b128 v[142:145], v140
	ds_read_b128 v[150:153], v140 offset:1024
	ds_read_b128 v[154:157], v140 offset:2048
	ds_read_b128 v[158:161], v140 offset:3072
	v_add_u32_e32 v140, s85, v146
	ds_read_b128 v[162:165], v140
	ds_read_b128 v[166:169], v140 offset:1024
	ds_read_b128 v[170:173], v140 offset:2048
	ds_read_b128 v[174:177], v140 offset:3072
	s_add_u32 s64, s64, 0x40000
	s_addc_u32 s65, s65, 0
	s_mov_b32 m0, s21
	v_lshl_add_u64 v[234:235], s[64:65], 0, v[134:135]
	ds_read_b128 v[178:181], v148 offset:32768
	ds_read_b128 v[182:185], v148 offset:33792
	ds_read_b128 v[190:193], v148 offset:34816
	ds_read_b128 v[194:197], v148 offset:35840
	ds_read_b128 v[198:201], v148 offset:36864
	ds_read_b128 v[202:205], v148 offset:37888
	ds_read_b128 v[206:209], v148 offset:38912
	ds_read_b128 v[228:231], v148 offset:39936
	global_load_lds_dwordx4 v[234:235], off
	v_lshl_add_u64 v[234:235], s[64:65], 0, v[132:133]
	s_mov_b32 m0, s22
	s_nop 0
	global_load_lds_dwordx4 v[234:235], off
	s_waitcnt vmcnt(8)
	s_waitcnt lgkmcnt(0)
	s_barrier
	s_waitcnt lgkmcnt(0)
	v_mfma_f32_16x16x32_bf16 v[124:127], v[142:145], v[178:181], v[124:127]
	v_mfma_f32_16x16x32_bf16 v[120:123], v[154:157], v[178:181], v[120:123]
	v_mfma_f32_16x16x32_bf16 v[116:119], v[142:145], v[190:193], v[116:119]
	v_mfma_f32_16x16x32_bf16 v[112:115], v[154:157], v[190:193], v[112:115]
	v_mfma_f32_16x16x32_bf16 v[108:111], v[142:145], v[198:201], v[108:111]
	v_mfma_f32_16x16x32_bf16 v[104:107], v[154:157], v[198:201], v[104:107]
	v_mfma_f32_16x16x32_bf16 v[100:103], v[142:145], v[206:209], v[100:103]
	v_mfma_f32_16x16x32_bf16 v[96:99], v[154:157], v[206:209], v[96:99]
	v_mfma_f32_16x16x32_bf16 v[124:127], v[150:153], v[182:185], v[124:127]
	v_mfma_f32_16x16x32_bf16 v[120:123], v[158:161], v[182:185], v[120:123]
	v_mfma_f32_16x16x32_bf16 v[116:119], v[150:153], v[194:197], v[116:119]
	v_mfma_f32_16x16x32_bf16 v[112:115], v[158:161], v[194:197], v[112:115]
	v_mfma_f32_16x16x32_bf16 v[108:111], v[150:153], v[202:205], v[108:111]
	v_mfma_f32_16x16x32_bf16 v[104:107], v[158:161], v[202:205], v[104:107]
	v_mfma_f32_16x16x32_bf16 v[100:103], v[150:153], v[228:231], v[100:103]
	v_mfma_f32_16x16x32_bf16 v[96:99], v[158:161], v[228:231], v[96:99]
	v_mfma_f32_16x16x32_bf16 v[92:95], v[162:165], v[178:181], v[92:95]
	v_mfma_f32_16x16x32_bf16 v[88:91], v[170:173], v[178:181], v[88:91]
	v_mfma_f32_16x16x32_bf16 v[84:87], v[162:165], v[190:193], v[84:87]
	v_mfma_f32_16x16x32_bf16 v[80:83], v[170:173], v[190:193], v[80:83]
	v_mfma_f32_16x16x32_bf16 v[76:79], v[162:165], v[198:201], v[76:79]
	v_mfma_f32_16x16x32_bf16 v[72:75], v[170:173], v[198:201], v[72:75]
	v_mfma_f32_16x16x32_bf16 v[68:71], v[162:165], v[206:209], v[68:71]
	v_mfma_f32_16x16x32_bf16 v[64:67], v[170:173], v[206:209], v[64:67]
	v_mfma_f32_16x16x32_bf16 v[92:95], v[166:169], v[182:185], v[92:95]
	v_mfma_f32_16x16x32_bf16 v[88:91], v[174:177], v[182:185], v[88:91]
	v_mfma_f32_16x16x32_bf16 v[84:87], v[166:169], v[194:197], v[84:87]
	v_mfma_f32_16x16x32_bf16 v[80:83], v[174:177], v[194:197], v[80:83]
	v_mfma_f32_16x16x32_bf16 v[76:79], v[166:169], v[202:205], v[76:79]
	v_mfma_f32_16x16x32_bf16 v[72:75], v[174:177], v[202:205], v[72:75]
	v_mfma_f32_16x16x32_bf16 v[68:71], v[166:169], v[228:231], v[68:71]
	v_mfma_f32_16x16x32_bf16 v[64:67], v[174:177], v[228:231], v[64:67]
	s_barrier
; #define PG8_STAGE(bufoff, gbase, voff) do { _Pragma("unroll") for (int _i = 0; _i < 2; ++_i) \
;         __builtin_amdgcn_global_load_lds((const unsigned*)((const char*)(gbase) + (voff)[_i]), (PG8_LAS unsigned*)(lds + (bufoff) + ldsw + _i * 8192), 16, 0, 0); } while (0)
; #define PG8_LDA(dst, b, h) do { _Pragma("unroll") for (int m = 0; m < 4; ++m) _Pragma("unroll") for (int k = 0; k < 2; ++k) dst[m][k] = *(const PG8_LAS bf16x8*)(lds + PG8_SA(b, h) + aoff + m * 2048 + k * 1024); } while (0)
; #define PG8_MMA(ai, bj, At, Bt) do { __builtin_amdgcn_s_setprio(1); _Pragma("unroll") for (int m = 0; m < 4; ++m) _Pragma("unroll") for (int n = 0; n < 2; ++n) _Pragma("unroll") for (int k = 0; k < 2; ++k) \
;         acc[ai][bj][m][n] = __builtin_amdgcn_mfma_f32_16x16x32_bf16(Bt[n][k], At[m][k], acc[ai][bj][m][n], 0, 0, 0); __builtin_amdgcn_s_setprio(0); } while (0)
; #define PG8_WAIT_V(n) asm volatile("s_waitcnt vmcnt(" #n ")" ::: "memory")
; #define PG8_WAIT_L(n) asm volatile("s_waitcnt lgkmcnt(" #n ")" ::: "memory")
; #define PG8_BAR __builtin_amdgcn_s_barrier()
; #define PG8_SCHED __builtin_amdgcn_sched_barrier(0)
; template <class Epi, class Sched, bool ALIGN_EPI = false, bool SP2 = false>
; __device__ __forceinline__ void gemm_phase(PG8_LAS unsigned char* lds, const Gemm g, const Sched& S, const Epi& E) {
;     ...
;             PG8_LDA(At, 1, 1); PG8_STAGE(PG8_SB(1, 0), b3, voffB); PG8_STAGE(PG8_SB(1, 1), b3 + hstep, voffB); PG8_STAGE(PG8_SA(1, 0), a3, voffA);
;             PG8_WAIT_V(8); PG8_WAIT_L(0); PG8_BAR; PG8_MMA(1, 0, At, B0); PG8_MMA(1, 1, At, B1); PG8_BAR; PG8_SCHED;
	s_add_i32 s64, s84, s18
	v_lshl_add_u64 v[186:187], v[186:187], 0, s[90:91]
	s_mov_b32 m0, s64
	ds_read_b128 v[178:181], v148 offset:49152
	ds_read_b128 v[182:185], v148 offset:50176
	ds_read_b128 v[190:193], v148 offset:51200
	ds_read_b128 v[194:197], v148 offset:52224
	ds_read_b128 v[198:201], v148 offset:53248
	ds_read_b128 v[202:205], v148 offset:54272
	ds_read_b128 v[206:209], v148 offset:55296
	ds_read_b128 v[228:231], v148 offset:56320
	global_load_lds_dwordx4 v[186:187], off
	s_add_i32 m0, s64, 0x2000
	s_add_u32 s58, s58, 0x40080
	v_lshl_add_u64 v[186:187], v[188:189], 0, s[90:91]
	s_addc_u32 s59, s59, 0
	s_add_i32 s64, s85, s18
	global_load_lds_dwordx4 v[186:187], off
	v_lshl_add_u64 v[186:187], s[58:59], 0, v[128:129]
	s_mov_b32 m0, s64
	s_nop 0
	global_load_lds_dwordx4 v[186:187], off
	v_lshl_add_u64 v[186:187], s[58:59], 0, v[130:131]
	s_add_i32 m0, s64, 0x2000
	s_nop 0
	global_load_lds_dwordx4 v[186:187], off
	v_lshl_add_u64 v[186:187], v[210:211], 0, s[90:91]
	s_mov_b32 m0, s28
	s_nop 0
	global_load_lds_dwordx4 v[186:187], off
	v_lshl_add_u64 v[186:187], v[232:233], 0, s[90:91]
	s_mov_b32 m0, s29
	s_nop 0
	global_load_lds_dwordx4 v[186:187], off
	s_waitcnt vmcnt(8)
	s_waitcnt lgkmcnt(0)
	s_barrier
	s_waitcnt lgkmcnt(0)
	v_mfma_f32_16x16x32_bf16 v[60:63], v[142:145], v[178:181], v[60:63]
	v_mfma_f32_16x16x32_bf16 v[56:59], v[154:157], v[178:181], v[56:59]
	v_mfma_f32_16x16x32_bf16 v[52:55], v[142:145], v[190:193], v[52:55]
	v_mfma_f32_16x16x32_bf16 v[48:51], v[154:157], v[190:193], v[48:51]
	v_mfma_f32_16x16x32_bf16 v[44:47], v[142:145], v[198:201], v[44:47]
	v_mfma_f32_16x16x32_bf16 v[40:43], v[154:157], v[198:201], v[40:43]
	v_mfma_f32_16x16x32_bf16 v[36:39], v[142:145], v[206:209], v[36:39]
	v_mfma_f32_16x16x32_bf16 v[32:35], v[154:157], v[206:209], v[32:35]
	v_mfma_f32_16x16x32_bf16 v[60:63], v[150:153], v[182:185], v[60:63]
	v_mfma_f32_16x16x32_bf16 v[56:59], v[158:161], v[182:185], v[56:59]
	v_mfma_f32_16x16x32_bf16 v[52:55], v[150:153], v[194:197], v[52:55]
	v_mfma_f32_16x16x32_bf16 v[48:51], v[158:161], v[194:197], v[48:51]
	v_mfma_f32_16x16x32_bf16 v[44:47], v[150:153], v[202:205], v[44:47]
	v_mfma_f32_16x16x32_bf16 v[40:43], v[158:161], v[202:205], v[40:43]
	v_mfma_f32_16x16x32_bf16 v[36:39], v[150:153], v[228:231], v[36:39]
	v_mfma_f32_16x16x32_bf16 v[32:35], v[158:161], v[228:231], v[32:35]
	v_mfma_f32_16x16x32_bf16 v[28:31], v[162:165], v[178:181], v[28:31]
	v_mfma_f32_16x16x32_bf16 v[24:27], v[170:173], v[178:181], v[24:27]
	v_mfma_f32_16x16x32_bf16 v[20:23], v[162:165], v[190:193], v[20:23]
	v_mfma_f32_16x16x32_bf16 v[16:19], v[170:173], v[190:193], v[16:19]
	v_mfma_f32_16x16x32_bf16 v[12:15], v[162:165], v[198:201], v[12:15]
	v_mfma_f32_16x16x32_bf16 v[8:11], v[170:173], v[198:201], v[8:11]
	v_mfma_f32_16x16x32_bf16 v[4:7], v[162:165], v[206:209], v[4:7]
	v_mfma_f32_16x16x32_bf16 v[0:3], v[170:173], v[206:209], v[0:3]
	v_mfma_f32_16x16x32_bf16 v[28:31], v[166:169], v[182:185], v[28:31]
	v_mfma_f32_16x16x32_bf16 v[24:27], v[174:177], v[182:185], v[24:27]
	v_mfma_f32_16x16x32_bf16 v[20:23], v[166:169], v[194:197], v[20:23]
	v_mfma_f32_16x16x32_bf16 v[16:19], v[174:177], v[194:197], v[16:19]
	v_mfma_f32_16x16x32_bf16 v[12:15], v[166:169], v[202:205], v[12:15]
	v_mfma_f32_16x16x32_bf16 v[8:11], v[174:177], v[202:205], v[8:11]
	v_mfma_f32_16x16x32_bf16 v[4:7], v[166:169], v[228:231], v[4:7]
	v_mfma_f32_16x16x32_bf16 v[0:3], v[174:177], v[228:231], v[0:3]
	s_barrier
	s_add_i32 s94, s94, 2
	s_add_u32 s72, s72, 0x100
	s_addc_u32 s73, s73, 0
	s_add_u32 s92, s92, 0x100
	s_addc_u32 s93, s93, 0
	s_cmp_gt_u32 s94, 13
	s_cbranch_scc1 .Lpeel_x1

; #define PG8_BAR __builtin_amdgcn_s_barrier()
; template <class Epi, class Sched, bool ALIGN_EPI = false, bool SP2 = false>
; __device__ __forceinline__ void gemm_phase(PG8_LAS unsigned char* lds, const Gemm g, const Sched& S, const Epi& E) {
;     ...
;         if constexpr (ALIGN_EPI) { if (wr == 0) PG8_BAR; }
.Lpeel_x1:
	s_setprio 0
	s_and_b64 vcc, exec, s[48:49]
	s_cbranch_vccz .LBB0_167
	s_barrier

; #define PG8_STAGE(bufoff, gbase, voff) do { _Pragma("unroll") for (int _i = 0; _i < 2; ++_i) \
;         __builtin_amdgcn_global_load_lds((const unsigned*)((const char*)(gbase) + (voff)[_i]), (PG8_LAS unsigned*)(lds + (bufoff) + ldsw + _i * 8192), 16, 0, 0); } while (0)
; #define PG8_LDA(dst, b, h) do { _Pragma("unroll") for (int m = 0; m < 4; ++m) _Pragma("unroll") for (int k = 0; k < 2; ++k) dst[m][k] = *(const PG8_LAS bf16x8*)(lds + PG8_SA(b, h) + aoff + m * 2048 + k * 1024); } while (0)
; #define PG8_LDB(dst, b, h) do { _Pragma("unroll") for (int n = 0; n < 2; ++n) _Pragma("unroll") for (int k = 0; k < 2; ++k) dst[n][k] = *(const PG8_LAS bf16x8*)(lds + PG8_SB(b, h) + boff + n * 2048 + k * 1024); } while (0)
; #define PG8_WAIT_V(n) asm volatile("s_waitcnt vmcnt(" #n ")" ::: "memory")
; #define PG8_WAIT_L(n) asm volatile("s_waitcnt lgkmcnt(" #n ")" ::: "memory")
; #define PG8_BAR __builtin_amdgcn_s_barrier()
; #define PG8_SCHED __builtin_amdgcn_sched_barrier(0)
; template <class Epi, class Sched, bool ALIGN_EPI = false, bool SP2 = false>
; __device__ __forceinline__ void gemm_phase(PG8_LAS unsigned char* lds, const Gemm g, const Sched& S, const Epi& E) {
;     ...
;         const bool has_next = S.next(ui + 1, nxt);
;         const char* nA = has_next ? (const char*)g.A + (size_t)nxt.pm * tstep : cA; const char* nB = has_next ? (const char*)g.Bt + (size_t)nxt.pn * tstep : cB;
;         for (int t = 0; t < nt; t += 2) {
;             const bool last = (t == nt - 2);
;             const char* a1 = cA + (size_t)(t + 1) * kstep;
;             const char* a2 = last ? nA : cA + (size_t)(t + 2) * kstep; const char* b2 = last ? nB : cB + (size_t)(t + 2) * kstep;
;             const char* a3 = a2 + kstep; const char* b3 = b2 + kstep;
;             if (last && has_next) S.a_ready(nxt);
;             if constexpr (SP2) {
;             PG8_LDB(B0, 0, 0); PG8_LDB(B1, 0, 1); PG8_SCHED; PG8_LDA(At, 0, 0); PG8_STAGE(PG8_SA(1, 1), a1 + hstep, voffA);
;             PG8_WAIT_V(8); PG8_WAIT_L(0); PG8_BAR; PG8_MMA(0, 0, At, B0); PG8_MMA(0, 1, At, B1); PG8_BAR; PG8_SCHED;
;             PG8_LDA(At, 0, 1); PG8_STAGE(PG8_SB(0, 0), b2, voffB); PG8_STAGE(PG8_SB(0, 1), b2 + hstep, voffB); PG8_STAGE(PG8_SA(0, 0), a2, voffA);
;             PG8_WAIT_V(8); PG8_WAIT_L(0); PG8_BAR; PG8_MMA(1, 0, At, B0); PG8_MMA(1, 1, At, B1); PG8_BAR; PG8_SCHED;
.LBB0_563:
	s_ashr_i32 s67, s66, 31
	s_lshl_b64 s[36:37], s[66:67], 19
	s_add_u32 s64, s2, s36
	s_addc_u32 s65, s25, s37
	s_and_b64 s[36:37], s[40:41], exec
	s_cselect_b32 s36, s65, s93
	s_cselect_b32 s37, s64, s92
	s_ashr_i32 s73, s72, 31
	s_lshl_b64 s[84:85], s[72:73], 19
	s_add_u32 s96, s70, s84
	s_addc_u32 s97, s16, s85
	s_and_b64 s[84:85], s[40:41], exec
	s_cselect_b32 s67, s97, s59
	s_cselect_b32 s73, s96, s58
	s_add_u32 vcc_lo, s92, 0x40080
	s_addc_u32 vcc_hi, s93, 0
	s_add_u32 s88, s58, 0x100
	s_addc_u32 s94, s59, 0
	s_mov_b32 s84, -2
	s_and_b64 s[98:99], exec, s[62:63]
	s_cbranch_scc1 .Lsp_2
	s_setprio 1
.Lsp_2:
	s_add_u32 s44, vcc_lo, 0xfffc0080
	s_addc_u32 s45, vcc_hi, -1
	s_add_i32 s85, 0, 0x10000
	s_cmp_eq_u32 s84, 12
	s_cselect_b32 s93, s36, s45
	s_cselect_b32 s92, s37, s44
	s_cselect_b32 s59, s67, s94
	s_cselect_b32 s58, s73, s88
	s_add_i32 s8, 0, 0x14000
	v_add_u32_e32 v142, s85, v201
	v_add_u32_e32 v168, s8, v201
	ds_read_b128 v[130:133], v142
	ds_read_b128 v[134:137], v142 offset:1024
	ds_read_b128 v[138:141], v142 offset:2048
	ds_read_b128 v[142:145], v142 offset:3072
	ds_read_b128 v[156:159], v168
	ds_read_b128 v[160:163], v168 offset:1024
	ds_read_b128 v[164:167], v168 offset:2048
	ds_read_b128 v[168:171], v168 offset:3072
	v_lshl_add_u64 v[208:209], vcc, 0, v[152:153]
	s_add_i32 m0, s15, 0xc000
	ds_read_b128 v[172:175], v203
	ds_read_b128 v[176:179], v203 offset:1024
	ds_read_b128 v[180:183], v203 offset:2048
	ds_read_b128 v[184:187], v203 offset:3072
	ds_read_b128 v[188:191], v203 offset:4096
	ds_read_b128 v[192:195], v203 offset:5120
	ds_read_b128 v[196:199], v203 offset:6144
	ds_read_b128 v[204:207], v203 offset:7168
	global_load_lds_dwordx4 v[208:209], off
	v_lshl_add_u64 v[208:209], vcc, 0, v[154:155]
	s_add_i32 m0, s15, 0xe000
	s_nop 0
	global_load_lds_dwordx4 v[208:209], off
	s_waitcnt vmcnt(8)
	s_waitcnt lgkmcnt(0)
	s_barrier
	s_waitcnt lgkmcnt(0)
	v_mfma_f32_16x16x32_bf16 v[124:127], v[130:133], v[172:175], 0
	v_mfma_f32_16x16x32_bf16 v[120:123], v[138:141], v[172:175], 0
	v_mfma_f32_16x16x32_bf16 v[108:111], v[130:133], v[180:183], 0
	v_mfma_f32_16x16x32_bf16 v[104:107], v[138:141], v[180:183], 0
	v_mfma_f32_16x16x32_bf16 v[92:95], v[130:133], v[188:191], 0
	v_mfma_f32_16x16x32_bf16 v[88:91], v[138:141], v[188:191], 0
	v_mfma_f32_16x16x32_bf16 v[76:79], v[130:133], v[196:199], 0
	v_mfma_f32_16x16x32_bf16 v[72:75], v[138:141], v[196:199], 0
	v_mfma_f32_16x16x32_bf16 v[124:127], v[134:137], v[176:179], v[124:127]
	v_mfma_f32_16x16x32_bf16 v[120:123], v[142:145], v[176:179], v[120:123]
	v_mfma_f32_16x16x32_bf16 v[108:111], v[134:137], v[184:187], v[108:111]
	v_mfma_f32_16x16x32_bf16 v[104:107], v[142:145], v[184:187], v[104:107]
	v_mfma_f32_16x16x32_bf16 v[92:95], v[134:137], v[192:195], v[92:95]
	v_mfma_f32_16x16x32_bf16 v[88:91], v[142:145], v[192:195], v[88:91]
	v_mfma_f32_16x16x32_bf16 v[76:79], v[134:137], v[204:207], v[76:79]
	v_mfma_f32_16x16x32_bf16 v[72:75], v[142:145], v[204:207], v[72:75]
	v_mfma_f32_16x16x32_bf16 v[116:119], v[156:159], v[172:175], 0
	v_mfma_f32_16x16x32_bf16 v[112:115], v[164:167], v[172:175], 0
	v_mfma_f32_16x16x32_bf16 v[100:103], v[156:159], v[180:183], 0
	v_mfma_f32_16x16x32_bf16 v[96:99], v[164:167], v[180:183], 0
	v_mfma_f32_16x16x32_bf16 v[84:87], v[156:159], v[188:191], 0
	v_mfma_f32_16x16x32_bf16 v[80:83], v[164:167], v[188:191], 0
	v_mfma_f32_16x16x32_bf16 v[68:71], v[156:159], v[196:199], 0
	v_mfma_f32_16x16x32_bf16 v[64:67], v[164:167], v[196:199], 0
	v_mfma_f32_16x16x32_bf16 v[116:119], v[160:163], v[176:179], v[116:119]
	v_mfma_f32_16x16x32_bf16 v[112:115], v[168:171], v[176:179], v[112:115]
	v_mfma_f32_16x16x32_bf16 v[100:103], v[160:163], v[184:187], v[100:103]
	v_mfma_f32_16x16x32_bf16 v[96:99], v[168:171], v[184:187], v[96:99]
	v_mfma_f32_16x16x32_bf16 v[84:87], v[160:163], v[192:195], v[84:87]
	v_mfma_f32_16x16x32_bf16 v[80:83], v[168:171], v[192:195], v[80:83]
	v_mfma_f32_16x16x32_bf16 v[68:71], v[160:163], v[204:207], v[68:71]
	v_mfma_f32_16x16x32_bf16 v[64:67], v[168:171], v[204:207], v[64:67]
	s_barrier
	s_add_i32 s44, s85, s14
	v_lshl_add_u64 v[208:209], s[58:59], 0, v[128:129]
	s_mov_b32 m0, s44
	ds_read_b128 v[172:175], v203 offset:16384
	ds_read_b128 v[176:179], v203 offset:17408
	ds_read_b128 v[180:183], v203 offset:18432
	ds_read_b128 v[184:187], v203 offset:19456
	ds_read_b128 v[188:191], v203 offset:20480
	ds_read_b128 v[192:195], v203 offset:21504
	ds_read_b128 v[196:199], v203 offset:22528
	ds_read_b128 v[204:207], v203 offset:23552
	global_load_lds_dwordx4 v[208:209], off
	s_add_i32 m0, s44, 0x2000
	s_add_u32 s44, s58, 0x40000
	v_lshl_add_u64 v[210:211], s[58:59], 0, v[146:147]
	s_addc_u32 s45, s59, 0
	s_add_i32 s8, s8, s14
	global_load_lds_dwordx4 v[210:211], off
	v_lshl_add_u64 v[214:215], s[44:45], 0, v[128:129]
	s_mov_b32 m0, s8
	v_lshl_add_u64 v[222:223], s[92:93], 0, v[148:149]
	global_load_lds_dwordx4 v[214:215], off
	v_lshl_add_u64 v[214:215], s[44:45], 0, v[146:147]
	s_add_i32 m0, s8, 0x2000
	s_nop 0
	global_load_lds_dwordx4 v[214:215], off
	v_lshl_add_u64 v[214:215], s[92:93], 0, v[150:151]
	s_mov_b32 m0, s15
	s_nop 0
	global_load_lds_dwordx4 v[214:215], off
	s_mov_b32 m0, s17
	s_nop 0
	global_load_lds_dwordx4 v[222:223], off
	s_waitcnt vmcnt(8)
	s_waitcnt lgkmcnt(0)
	s_barrier
; #define PG8_STAGE(bufoff, gbase, voff) do { _Pragma("unroll") for (int _i = 0; _i < 2; ++_i) \
;         __builtin_amdgcn_global_load_lds((const unsigned*)((const char*)(gbase) + (voff)[_i]), (PG8_LAS unsigned*)(lds + (bufoff) + ldsw + _i * 8192), 16, 0, 0); } while (0)
; #define PG8_LDA(dst, b, h) do { _Pragma("unroll") for (int m = 0; m < 4; ++m) _Pragma("unroll") for (int k = 0; k < 2; ++k) dst[m][k] = *(const PG8_LAS bf16x8*)(lds + PG8_SA(b, h) + aoff + m * 2048 + k * 1024); } while (0)
; #define PG8_LDB(dst, b, h) do { _Pragma("unroll") for (int n = 0; n < 2; ++n) _Pragma("unroll") for (int k = 0; k < 2; ++k) dst[n][k] = *(const PG8_LAS bf16x8*)(lds + PG8_SB(b, h) + boff + n * 2048 + k * 1024); } while (0)
; #define PG8_MMA(ai, bj, At, Bt) do { __builtin_amdgcn_s_setprio(1); _Pragma("unroll") for (int m = 0; m < 4; ++m) _Pragma("unroll") for (int n = 0; n < 2; ++n) _Pragma("unroll") for (int k = 0; k < 2; ++k) \
;         acc[ai][bj][m][n] = __builtin_amdgcn_mfma_f32_16x16x32_bf16(Bt[n][k], At[m][k], acc[ai][bj][m][n], 0, 0, 0); __builtin_amdgcn_s_setprio(0); } while (0)
; #define PG8_WAIT_V(n) asm volatile("s_waitcnt vmcnt(" #n ")" ::: "memory")
; #define PG8_WAIT_L(n) asm volatile("s_waitcnt lgkmcnt(" #n ")" ::: "memory")
; #define PG8_BAR __builtin_amdgcn_s_barrier()
; #define PG8_SCHED __builtin_amdgcn_sched_barrier(0)
; template <class Epi, class Sched, bool ALIGN_EPI = false, bool SP2 = false>
; __device__ __forceinline__ void gemm_phase(PG8_LAS unsigned char* lds, const Gemm g, const Sched& S, const Epi& E) {
;     ...
;             PG8_WAIT_V(8); PG8_WAIT_L(0); PG8_BAR; PG8_MMA(1, 0, At, B0); PG8_MMA(1, 1, At, B1); PG8_BAR; PG8_SCHED;
;             PG8_LDB(B0, 1, 0); PG8_LDB(B1, 1, 1); PG8_SCHED; PG8_LDA(At, 1, 0); PG8_STAGE(PG8_SA(0, 1), a2 + hstep, voffA);
;             PG8_WAIT_V(8); PG8_WAIT_L(0); PG8_BAR; PG8_MMA(0, 0, At, B0); PG8_MMA(0, 1, At, B1); PG8_BAR; PG8_SCHED;
	s_waitcnt lgkmcnt(0)
	v_mfma_f32_16x16x32_bf16 v[60:63], v[130:133], v[172:175], 0
	v_mfma_f32_16x16x32_bf16 v[56:59], v[138:141], v[172:175], 0
	v_mfma_f32_16x16x32_bf16 v[44:47], v[130:133], v[180:183], 0
	v_mfma_f32_16x16x32_bf16 v[40:43], v[138:141], v[180:183], 0
	v_mfma_f32_16x16x32_bf16 v[28:31], v[130:133], v[188:191], 0
	v_mfma_f32_16x16x32_bf16 v[24:27], v[138:141], v[188:191], 0
	v_mfma_f32_16x16x32_bf16 v[12:15], v[130:133], v[196:199], 0
	v_mfma_f32_16x16x32_bf16 v[8:11], v[138:141], v[196:199], 0
	v_mfma_f32_16x16x32_bf16 v[60:63], v[134:137], v[176:179], v[60:63]
	v_mfma_f32_16x16x32_bf16 v[56:59], v[142:145], v[176:179], v[56:59]
	v_mfma_f32_16x16x32_bf16 v[44:47], v[134:137], v[184:187], v[44:47]
	v_mfma_f32_16x16x32_bf16 v[40:43], v[142:145], v[184:187], v[40:43]
	v_mfma_f32_16x16x32_bf16 v[28:31], v[134:137], v[192:195], v[28:31]
	v_mfma_f32_16x16x32_bf16 v[24:27], v[142:145], v[192:195], v[24:27]
	v_mfma_f32_16x16x32_bf16 v[12:15], v[134:137], v[204:207], v[12:15]
	v_mfma_f32_16x16x32_bf16 v[8:11], v[142:145], v[204:207], v[8:11]
	v_mfma_f32_16x16x32_bf16 v[52:55], v[156:159], v[172:175], 0
	v_mfma_f32_16x16x32_bf16 v[48:51], v[164:167], v[172:175], 0
	v_mfma_f32_16x16x32_bf16 v[36:39], v[156:159], v[180:183], 0
	v_mfma_f32_16x16x32_bf16 v[32:35], v[164:167], v[180:183], 0
	v_mfma_f32_16x16x32_bf16 v[20:23], v[156:159], v[188:191], 0
	v_mfma_f32_16x16x32_bf16 v[16:19], v[164:167], v[188:191], 0
	v_mfma_f32_16x16x32_bf16 v[4:7], v[156:159], v[196:199], 0
	v_mfma_f32_16x16x32_bf16 v[0:3], v[164:167], v[196:199], 0
	v_mfma_f32_16x16x32_bf16 v[52:55], v[160:163], v[176:179], v[52:55]
	v_mfma_f32_16x16x32_bf16 v[48:51], v[168:171], v[176:179], v[48:51]
	v_mfma_f32_16x16x32_bf16 v[36:39], v[160:163], v[184:187], v[36:39]
	v_mfma_f32_16x16x32_bf16 v[32:35], v[168:171], v[184:187], v[32:35]
	v_mfma_f32_16x16x32_bf16 v[20:23], v[160:163], v[192:195], v[20:23]
	v_mfma_f32_16x16x32_bf16 v[16:19], v[168:171], v[192:195], v[16:19]
	v_mfma_f32_16x16x32_bf16 v[4:7], v[160:163], v[204:207], v[4:7]
	v_mfma_f32_16x16x32_bf16 v[0:3], v[168:171], v[204:207], v[0:3]
	s_barrier
	s_add_i32 s8, 0, 0x18000
	s_add_i32 s85, 0, 0x1c000
	v_add_u32_e32 v142, s8, v201
	v_add_u32_e32 v168, s85, v201
	ds_read_b128 v[130:133], v142
	ds_read_b128 v[134:137], v142 offset:1024
	ds_read_b128 v[138:141], v142 offset:2048
	ds_read_b128 v[142:145], v142 offset:3072
	ds_read_b128 v[156:159], v168
	ds_read_b128 v[160:163], v168 offset:1024
	ds_read_b128 v[164:167], v168 offset:2048
	ds_read_b128 v[168:171], v168 offset:3072
	s_add_u32 s44, s92, 0x40000
	s_addc_u32 s45, s93, 0
	s_mov_b32 m0, s18
	v_lshl_add_u64 v[228:229], s[44:45], 0, v[150:151]
	ds_read_b128 v[172:175], v203 offset:32768
	ds_read_b128 v[176:179], v203 offset:33792
	ds_read_b128 v[180:183], v203 offset:34816
	ds_read_b128 v[184:187], v203 offset:35840
	ds_read_b128 v[188:191], v203 offset:36864
	ds_read_b128 v[192:195], v203 offset:37888
	ds_read_b128 v[196:199], v203 offset:38912
	ds_read_b128 v[204:207], v203 offset:39936
	global_load_lds_dwordx4 v[228:229], off
	v_lshl_add_u64 v[228:229], s[44:45], 0, v[148:149]
	s_mov_b32 m0, s19
	s_nop 0
	global_load_lds_dwordx4 v[228:229], off
	s_waitcnt vmcnt(8)
	s_waitcnt lgkmcnt(0)
	s_barrier
	s_waitcnt lgkmcnt(0)
	v_mfma_f32_16x16x32_bf16 v[124:127], v[130:133], v[172:175], v[124:127]
	v_mfma_f32_16x16x32_bf16 v[120:123], v[138:141], v[172:175], v[120:123]
	v_mfma_f32_16x16x32_bf16 v[108:111], v[130:133], v[180:183], v[108:111]
	v_mfma_f32_16x16x32_bf16 v[104:107], v[138:141], v[180:183], v[104:107]
	v_mfma_f32_16x16x32_bf16 v[92:95], v[130:133], v[188:191], v[92:95]
	v_mfma_f32_16x16x32_bf16 v[88:91], v[138:141], v[188:191], v[88:91]
	v_mfma_f32_16x16x32_bf16 v[76:79], v[130:133], v[196:199], v[76:79]
	v_mfma_f32_16x16x32_bf16 v[72:75], v[138:141], v[196:199], v[72:75]
	v_mfma_f32_16x16x32_bf16 v[124:127], v[134:137], v[176:179], v[124:127]
	v_mfma_f32_16x16x32_bf16 v[120:123], v[142:145], v[176:179], v[120:123]
	v_mfma_f32_16x16x32_bf16 v[108:111], v[134:137], v[184:187], v[108:111]
	v_mfma_f32_16x16x32_bf16 v[104:107], v[142:145], v[184:187], v[104:107]
	v_mfma_f32_16x16x32_bf16 v[92:95], v[134:137], v[192:195], v[92:95]
	v_mfma_f32_16x16x32_bf16 v[88:91], v[142:145], v[192:195], v[88:91]
	v_mfma_f32_16x16x32_bf16 v[76:79], v[134:137], v[204:207], v[76:79]
	v_mfma_f32_16x16x32_bf16 v[72:75], v[142:145], v[204:207], v[72:75]
	v_mfma_f32_16x16x32_bf16 v[116:119], v[156:159], v[172:175], v[116:119]
	v_mfma_f32_16x16x32_bf16 v[112:115], v[164:167], v[172:175], v[112:115]
	v_mfma_f32_16x16x32_bf16 v[100:103], v[156:159], v[180:183], v[100:103]
	v_mfma_f32_16x16x32_bf16 v[96:99], v[164:167], v[180:183], v[96:99]
	v_mfma_f32_16x16x32_bf16 v[84:87], v[156:159], v[188:191], v[84:87]
	v_mfma_f32_16x16x32_bf16 v[80:83], v[164:167], v[188:191], v[80:83]
	v_mfma_f32_16x16x32_bf16 v[68:71], v[156:159], v[196:199], v[68:71]
	v_mfma_f32_16x16x32_bf16 v[64:67], v[164:167], v[196:199], v[64:67]
	v_mfma_f32_16x16x32_bf16 v[116:119], v[160:163], v[176:179], v[116:119]
	v_mfma_f32_16x16x32_bf16 v[112:115], v[168:171], v[176:179], v[112:115]
	v_mfma_f32_16x16x32_bf16 v[100:103], v[160:163], v[184:187], v[100:103]
	v_mfma_f32_16x16x32_bf16 v[96:99], v[168:171], v[184:187], v[96:99]
	v_mfma_f32_16x16x32_bf16 v[84:87], v[160:163], v[192:195], v[84:87]
	v_mfma_f32_16x16x32_bf16 v[80:83], v[168:171], v[192:195], v[80:83]
	v_mfma_f32_16x16x32_bf16 v[68:71], v[160:163], v[204:207], v[68:71]
	v_mfma_f32_16x16x32_bf16 v[64:67], v[168:171], v[204:207], v[64:67]
	s_barrier
; #define PG8_STAGE(bufoff, gbase, voff) do { _Pragma("unroll") for (int _i = 0; _i < 2; ++_i) \
;         __builtin_amdgcn_global_load_lds((const unsigned*)((const char*)(gbase) + (voff)[_i]), (PG8_LAS unsigned*)(lds + (bufoff) + ldsw + _i * 8192), 16, 0, 0); } while (0)
; #define PG8_LDA(dst, b, h) do { _Pragma("unroll") for (int m = 0; m < 4; ++m) _Pragma("unroll") for (int k = 0; k < 2; ++k) dst[m][k] = *(const PG8_LAS bf16x8*)(lds + PG8_SA(b, h) + aoff + m * 2048 + k * 1024); } while (0)
; #define PG8_MMA(ai, bj, At, Bt) do { __builtin_amdgcn_s_setprio(1); _Pragma("unroll") for (int m = 0; m < 4; ++m) _Pragma("unroll") for (int n = 0; n < 2; ++n) _Pragma("unroll") for (int k = 0; k < 2; ++k) \
;         acc[ai][bj][m][n] = __builtin_amdgcn_mfma_f32_16x16x32_bf16(Bt[n][k], At[m][k], acc[ai][bj][m][n], 0, 0, 0); __builtin_amdgcn_s_setprio(0); } while (0)
; #define PG8_WAIT_V(n) asm volatile("s_waitcnt vmcnt(" #n ")" ::: "memory")
; #define PG8_WAIT_L(n) asm volatile("s_waitcnt lgkmcnt(" #n ")" ::: "memory")
; #define PG8_BAR __builtin_amdgcn_s_barrier()
; #define PG8_SCHED __builtin_amdgcn_sched_barrier(0)
; template <class Epi, class Sched, bool ALIGN_EPI = false, bool SP2 = false>
; __device__ __forceinline__ void gemm_phase(PG8_LAS unsigned char* lds, const Gemm g, const Sched& S, const Epi& E) {
;     ...
;             PG8_LDA(At, 1, 1); PG8_STAGE(PG8_SB(1, 0), b3, voffB); PG8_STAGE(PG8_SB(1, 1), b3 + hstep, voffB); PG8_STAGE(PG8_SA(1, 0), a3, voffA);
;             PG8_WAIT_V(8); PG8_WAIT_L(0); PG8_BAR; PG8_MMA(1, 0, At, B0); PG8_MMA(1, 1, At, B1); PG8_BAR; PG8_SCHED;
	s_add_i32 s8, s8, s14
	v_lshl_add_u64 v[208:209], v[208:209], 0, s[90:91]
	s_mov_b32 m0, s8
	ds_read_b128 v[172:175], v203 offset:49152
	ds_read_b128 v[176:179], v203 offset:50176
	ds_read_b128 v[180:183], v203 offset:51200
	ds_read_b128 v[184:187], v203 offset:52224
	ds_read_b128 v[188:191], v203 offset:53248
	ds_read_b128 v[192:195], v203 offset:54272
	ds_read_b128 v[196:199], v203 offset:55296
	ds_read_b128 v[204:207], v203 offset:56320
	global_load_lds_dwordx4 v[208:209], off
	s_add_i32 m0, s8, 0x2000
	s_add_u32 s44, s58, 0x40080
	v_lshl_add_u64 v[208:209], v[210:211], 0, s[90:91]
	s_addc_u32 s45, s59, 0
	s_add_i32 s8, s85, s14
	global_load_lds_dwordx4 v[208:209], off
	v_lshl_add_u64 v[208:209], s[44:45], 0, v[128:129]
	s_mov_b32 m0, s8
	s_nop 0
	global_load_lds_dwordx4 v[208:209], off
	v_lshl_add_u64 v[208:209], s[44:45], 0, v[146:147]
	s_add_i32 m0, s8, 0x2000
	s_nop 0
	global_load_lds_dwordx4 v[208:209], off
	v_lshl_add_u64 v[208:209], v[214:215], 0, s[90:91]
	s_mov_b32 m0, s30
	s_nop 0
	global_load_lds_dwordx4 v[208:209], off
	v_lshl_add_u64 v[208:209], v[222:223], 0, s[90:91]
	s_mov_b32 m0, s31
	s_nop 0
	global_load_lds_dwordx4 v[208:209], off
	s_waitcnt vmcnt(8)
	s_waitcnt lgkmcnt(0)
	s_barrier
	s_waitcnt lgkmcnt(0)
	v_mfma_f32_16x16x32_bf16 v[60:63], v[130:133], v[172:175], v[60:63]
	v_mfma_f32_16x16x32_bf16 v[56:59], v[138:141], v[172:175], v[56:59]
	v_mfma_f32_16x16x32_bf16 v[44:47], v[130:133], v[180:183], v[44:47]
	v_mfma_f32_16x16x32_bf16 v[40:43], v[138:141], v[180:183], v[40:43]
	v_mfma_f32_16x16x32_bf16 v[28:31], v[130:133], v[188:191], v[28:31]
	v_mfma_f32_16x16x32_bf16 v[24:27], v[138:141], v[188:191], v[24:27]
	v_mfma_f32_16x16x32_bf16 v[12:15], v[130:133], v[196:199], v[12:15]
	v_mfma_f32_16x16x32_bf16 v[8:11], v[138:141], v[196:199], v[8:11]
	v_mfma_f32_16x16x32_bf16 v[60:63], v[134:137], v[176:179], v[60:63]
	v_mfma_f32_16x16x32_bf16 v[56:59], v[142:145], v[176:179], v[56:59]
	v_mfma_f32_16x16x32_bf16 v[44:47], v[134:137], v[184:187], v[44:47]
	v_mfma_f32_16x16x32_bf16 v[40:43], v[142:145], v[184:187], v[40:43]
	v_mfma_f32_16x16x32_bf16 v[28:31], v[134:137], v[192:195], v[28:31]
	v_mfma_f32_16x16x32_bf16 v[24:27], v[142:145], v[192:195], v[24:27]
	v_mfma_f32_16x16x32_bf16 v[12:15], v[134:137], v[204:207], v[12:15]
	v_mfma_f32_16x16x32_bf16 v[8:11], v[142:145], v[204:207], v[8:11]
	v_mfma_f32_16x16x32_bf16 v[52:55], v[156:159], v[172:175], v[52:55]
	v_mfma_f32_16x16x32_bf16 v[48:51], v[164:167], v[172:175], v[48:51]
	v_mfma_f32_16x16x32_bf16 v[36:39], v[156:159], v[180:183], v[36:39]
	v_mfma_f32_16x16x32_bf16 v[32:35], v[164:167], v[180:183], v[32:35]
	v_mfma_f32_16x16x32_bf16 v[20:23], v[156:159], v[188:191], v[20:23]
	v_mfma_f32_16x16x32_bf16 v[16:19], v[164:167], v[188:191], v[16:19]
	v_mfma_f32_16x16x32_bf16 v[4:7], v[156:159], v[196:199], v[4:7]
	v_mfma_f32_16x16x32_bf16 v[0:3], v[164:167], v[196:199], v[0:3]
	v_mfma_f32_16x16x32_bf16 v[52:55], v[160:163], v[176:179], v[52:55]
	v_mfma_f32_16x16x32_bf16 v[48:51], v[168:171], v[176:179], v[48:51]
	v_mfma_f32_16x16x32_bf16 v[36:39], v[160:163], v[184:187], v[36:39]
	v_mfma_f32_16x16x32_bf16 v[32:35], v[168:171], v[184:187], v[32:35]
	v_mfma_f32_16x16x32_bf16 v[20:23], v[160:163], v[192:195], v[20:23]
	v_mfma_f32_16x16x32_bf16 v[16:19], v[168:171], v[192:195], v[16:19]
	v_mfma_f32_16x16x32_bf16 v[4:7], v[160:163], v[204:207], v[4:7]
	v_mfma_f32_16x16x32_bf16 v[0:3], v[168:171], v[204:207], v[0:3]
	s_barrier
	s_add_i32 s84, s84, 2
	s_add_u32 vcc_lo, vcc_lo, 0x100
	s_addc_u32 vcc_hi, vcc_hi, 0
	s_add_u32 s88, s88, 0x100
	s_addc_u32 s94, s94, 0
	s_cmp_gt_u32 s84, 13
	s_cbranch_scc1 .Lpeel_x2

; #define PG8_BAR __builtin_amdgcn_s_barrier()
; template <class Epi, class Sched, bool ALIGN_EPI = false, bool SP2 = false>
; __device__ __forceinline__ void gemm_phase(PG8_LAS unsigned char* lds, const Gemm g, const Sched& S, const Epi& E) {
;     ...
;         if constexpr (ALIGN_EPI) { if (wr == 0) PG8_BAR; }
.Lpeel_x2:
	s_setprio 0
	s_and_b64 vcc, exec, s[62:63]
	s_cbranch_vccz .LBB0_567
	s_barrier

; #define PG8_STAGE(bufoff, gbase, voff) do { _Pragma("unroll") for (int _i = 0; _i < 2; ++_i) \
;         __builtin_amdgcn_global_load_lds((const unsigned*)((const char*)(gbase) + (voff)[_i]), (PG8_LAS unsigned*)(lds + (bufoff) + ldsw + _i * 8192), 16, 0, 0); } while (0)
; #define PG8_LDA(dst, b, h) do { _Pragma("unroll") for (int m = 0; m < 4; ++m) _Pragma("unroll") for (int k = 0; k < 2; ++k) dst[m][k] = *(const PG8_LAS bf16x8*)(lds + PG8_SA(b, h) + aoff + m * 2048 + k * 1024); } while (0)
; #define PG8_LDB(dst, b, h) do { _Pragma("unroll") for (int n = 0; n < 2; ++n) _Pragma("unroll") for (int k = 0; k < 2; ++k) dst[n][k] = *(const PG8_LAS bf16x8*)(lds + PG8_SB(b, h) + boff + n * 2048 + k * 1024); } while (0)
; #define PG8_WAIT_V(n) asm volatile("s_waitcnt vmcnt(" #n ")" ::: "memory")
; #define PG8_WAIT_L(n) asm volatile("s_waitcnt lgkmcnt(" #n ")" ::: "memory")
; #define PG8_BAR __builtin_amdgcn_s_barrier()
; #define PG8_SCHED __builtin_amdgcn_sched_barrier(0)
; template <class Epi, class Sched, bool ALIGN_EPI = false, bool SP2 = false>
; __device__ __forceinline__ void gemm_phase(PG8_LAS unsigned char* lds, const Gemm g, const Sched& S, const Epi& E) {
;     ...
;         const bool has_next = S.next(ui + 1, nxt);
;         const char* nA = has_next ? (const char*)g.A + (size_t)nxt.pm * tstep : cA; const char* nB = has_next ? (const char*)g.Bt + (size_t)nxt.pn * tstep : cB;
;         for (int t = 0; t < nt; t += 2) {
;             const bool last = (t == nt - 2);
;             const char* a1 = cA + (size_t)(t + 1) * kstep;
;             const char* a2 = last ? nA : cA + (size_t)(t + 2) * kstep; const char* b2 = last ? nB : cB + (size_t)(t + 2) * kstep;
;             const char* a3 = a2 + kstep; const char* b3 = b2 + kstep;
;             if (last && has_next) S.a_ready(nxt);
;             if constexpr (SP2) {
;             PG8_LDB(B0, 0, 0); PG8_LDB(B1, 0, 1); PG8_SCHED; PG8_LDA(At, 0, 0); PG8_STAGE(PG8_SA(1, 1), a1 + hstep, voffA);
;             PG8_WAIT_V(8); PG8_WAIT_L(0); PG8_BAR; PG8_MMA(0, 0, At, B0); PG8_MMA(0, 1, At, B1); PG8_BAR; PG8_SCHED;
;             PG8_LDA(At, 0, 1); PG8_STAGE(PG8_SB(0, 0), b2, voffB); PG8_STAGE(PG8_SB(0, 1), b2 + hstep, voffB); PG8_STAGE(PG8_SA(0, 0), a2, voffA);
;             PG8_WAIT_V(8); PG8_WAIT_L(0); PG8_BAR; PG8_MMA(1, 0, At, B0); PG8_MMA(1, 1, At, B1); PG8_BAR; PG8_SCHED;
.LBB0_597:
	s_ashr_i32 s93, s92, 31
	s_lshl_b64 s[36:37], s[92:93], 19
	s_add_u32 s44, s2, s36
	s_addc_u32 s45, s25, s37
	s_and_b64 s[36:37], s[40:41], exec
	s_cselect_b32 s35, s45, s65
	s_cselect_b32 s36, s44, s64
	s_ashr_i32 s97, s96, 31
	s_lshl_b64 s[62:63], s[96:97], 19
	s_add_u32 s62, s70, s62
	s_addc_u32 s63, s16, s63
	s_and_b64 s[84:85], s[40:41], exec
	s_cselect_b32 s37, s63, s59
	s_cselect_b32 s43, s62, s58
	s_add_u32 vcc_lo, s64, 0x40080
	s_addc_u32 vcc_hi, s65, 0
	s_add_u32 s88, s58, 0x100
	s_addc_u32 s93, s59, 0
	s_mov_b32 s94, -2
	s_and_b64 s[98:99], exec, s[72:73]
	s_cbranch_scc1 .Lsp_3
	s_setprio 1
.Lsp_3:
	s_add_u32 s58, vcc_lo, 0xfffc0080
	s_addc_u32 s59, vcc_hi, -1
	s_add_i32 s84, 0, 0x10000
	s_cmp_eq_u32 s94, 12
	s_cselect_b32 s65, s35, s59
	s_cselect_b32 s64, s36, s58
	s_cselect_b32 s59, s37, s93
	s_cselect_b32 s58, s43, s88
	s_add_i32 s97, 0, 0x14000
	v_add_u32_e32 v76, s84, v228
	v_add_u32_e32 v168, s97, v228
	ds_read_b128 v[64:67], v76
	ds_read_b128 v[68:71], v76 offset:1024
	ds_read_b128 v[72:75], v76 offset:2048
	ds_read_b128 v[76:79], v76 offset:3072
	ds_read_b128 v[156:159], v168
	ds_read_b128 v[160:163], v168 offset:1024
	ds_read_b128 v[164:167], v168 offset:2048
	ds_read_b128 v[168:171], v168 offset:3072
	v_lshl_add_u64 v[204:205], vcc, 0, v[152:153]
	s_add_i32 m0, s18, 0xc000
	ds_read_b128 v[172:175], v230
	ds_read_b128 v[176:179], v230 offset:1024
	ds_read_b128 v[180:183], v230 offset:2048
	ds_read_b128 v[184:187], v230 offset:3072
	ds_read_b128 v[188:191], v230 offset:4096
	ds_read_b128 v[192:195], v230 offset:5120
	ds_read_b128 v[196:199], v230 offset:6144
	ds_read_b128 v[200:203], v230 offset:7168
	global_load_lds_dwordx4 v[204:205], off
	v_lshl_add_u64 v[204:205], vcc, 0, v[154:155]
	s_add_i32 m0, s18, 0xe000
	s_nop 0
	global_load_lds_dwordx4 v[204:205], off
	s_waitcnt vmcnt(8)
	s_waitcnt lgkmcnt(0)
	s_barrier
	s_waitcnt lgkmcnt(0)
	v_mfma_f32_16x16x32_bf16 v[142:145], v[64:67], v[172:175], 0
	v_mfma_f32_16x16x32_bf16 v[138:141], v[72:75], v[172:175], 0
	v_mfma_f32_16x16x32_bf16 v[134:137], v[64:67], v[180:183], 0
	v_mfma_f32_16x16x32_bf16 v[124:127], v[72:75], v[180:183], 0
	v_mfma_f32_16x16x32_bf16 v[108:111], v[64:67], v[188:191], 0
	v_mfma_f32_16x16x32_bf16 v[104:107], v[72:75], v[188:191], 0
	v_mfma_f32_16x16x32_bf16 v[100:103], v[64:67], v[196:199], 0
	v_mfma_f32_16x16x32_bf16 v[92:95], v[72:75], v[196:199], 0
	v_mfma_f32_16x16x32_bf16 v[142:145], v[68:71], v[176:179], v[142:145]
	v_mfma_f32_16x16x32_bf16 v[138:141], v[76:79], v[176:179], v[138:141]
	v_mfma_f32_16x16x32_bf16 v[134:137], v[68:71], v[184:187], v[134:137]
	v_mfma_f32_16x16x32_bf16 v[124:127], v[76:79], v[184:187], v[124:127]
	v_mfma_f32_16x16x32_bf16 v[108:111], v[68:71], v[192:195], v[108:111]
	v_mfma_f32_16x16x32_bf16 v[104:107], v[76:79], v[192:195], v[104:107]
	v_mfma_f32_16x16x32_bf16 v[100:103], v[68:71], v[200:203], v[100:103]
	v_mfma_f32_16x16x32_bf16 v[92:95], v[76:79], v[200:203], v[92:95]
	v_mfma_f32_16x16x32_bf16 v[130:133], v[156:159], v[172:175], 0
	v_mfma_f32_16x16x32_bf16 v[120:123], v[164:167], v[172:175], 0
	v_mfma_f32_16x16x32_bf16 v[116:119], v[156:159], v[180:183], 0
	v_mfma_f32_16x16x32_bf16 v[112:115], v[164:167], v[180:183], 0
	v_mfma_f32_16x16x32_bf16 v[96:99], v[156:159], v[188:191], 0
	v_mfma_f32_16x16x32_bf16 v[88:91], v[164:167], v[188:191], 0
	v_mfma_f32_16x16x32_bf16 v[84:87], v[156:159], v[196:199], 0
	v_mfma_f32_16x16x32_bf16 v[80:83], v[164:167], v[196:199], 0
	v_mfma_f32_16x16x32_bf16 v[130:133], v[160:163], v[176:179], v[130:133]
	v_mfma_f32_16x16x32_bf16 v[120:123], v[168:171], v[176:179], v[120:123]
	v_mfma_f32_16x16x32_bf16 v[116:119], v[160:163], v[184:187], v[116:119]
	v_mfma_f32_16x16x32_bf16 v[112:115], v[168:171], v[184:187], v[112:115]
	v_mfma_f32_16x16x32_bf16 v[96:99], v[160:163], v[192:195], v[96:99]
	v_mfma_f32_16x16x32_bf16 v[88:91], v[168:171], v[192:195], v[88:91]
	v_mfma_f32_16x16x32_bf16 v[84:87], v[160:163], v[200:203], v[84:87]
	v_mfma_f32_16x16x32_bf16 v[80:83], v[168:171], v[200:203], v[80:83]
	s_barrier
	s_add_i32 s84, s84, s17
	v_lshl_add_u64 v[204:205], s[58:59], 0, v[128:129]
	s_mov_b32 m0, s84
	ds_read_b128 v[172:175], v230 offset:16384
	ds_read_b128 v[176:179], v230 offset:17408
	ds_read_b128 v[180:183], v230 offset:18432
	ds_read_b128 v[184:187], v230 offset:19456
	ds_read_b128 v[188:191], v230 offset:20480
	ds_read_b128 v[192:195], v230 offset:21504
	ds_read_b128 v[196:199], v230 offset:22528
	ds_read_b128 v[200:203], v230 offset:23552
	global_load_lds_dwordx4 v[204:205], off
	s_add_i32 m0, s84, 0x2000
	s_add_u32 s84, s58, 0x40000
	v_lshl_add_u64 v[206:207], s[58:59], 0, v[146:147]
	s_addc_u32 s85, s59, 0
	s_add_i32 s97, s97, s17
	global_load_lds_dwordx4 v[206:207], off
	v_lshl_add_u64 v[208:209], s[84:85], 0, v[128:129]
	s_mov_b32 m0, s97
	v_lshl_add_u64 v[210:211], s[64:65], 0, v[148:149]
	global_load_lds_dwordx4 v[208:209], off
	v_lshl_add_u64 v[208:209], s[84:85], 0, v[146:147]
	s_add_i32 m0, s97, 0x2000
	s_nop 0
	global_load_lds_dwordx4 v[208:209], off
	v_lshl_add_u64 v[208:209], s[64:65], 0, v[150:151]
	s_mov_b32 m0, s18
	s_nop 0
	global_load_lds_dwordx4 v[208:209], off
	s_mov_b32 m0, s19
	s_nop 0
	global_load_lds_dwordx4 v[210:211], off
	s_waitcnt vmcnt(8)
	s_waitcnt lgkmcnt(0)
	s_barrier
; #define PG8_STAGE(bufoff, gbase, voff) do { _Pragma("unroll") for (int _i = 0; _i < 2; ++_i) \
;         __builtin_amdgcn_global_load_lds((const unsigned*)((const char*)(gbase) + (voff)[_i]), (PG8_LAS unsigned*)(lds + (bufoff) + ldsw + _i * 8192), 16, 0, 0); } while (0)
; #define PG8_LDA(dst, b, h) do { _Pragma("unroll") for (int m = 0; m < 4; ++m) _Pragma("unroll") for (int k = 0; k < 2; ++k) dst[m][k] = *(const PG8_LAS bf16x8*)(lds + PG8_SA(b, h) + aoff + m * 2048 + k * 1024); } while (0)
; #define PG8_LDB(dst, b, h) do { _Pragma("unroll") for (int n = 0; n < 2; ++n) _Pragma("unroll") for (int k = 0; k < 2; ++k) dst[n][k] = *(const PG8_LAS bf16x8*)(lds + PG8_SB(b, h) + boff + n * 2048 + k * 1024); } while (0)
; #define PG8_MMA(ai, bj, At, Bt) do { __builtin_amdgcn_s_setprio(1); _Pragma("unroll") for (int m = 0; m < 4; ++m) _Pragma("unroll") for (int n = 0; n < 2; ++n) _Pragma("unroll") for (int k = 0; k < 2; ++k) \
;         acc[ai][bj][m][n] = __builtin_amdgcn_mfma_f32_16x16x32_bf16(Bt[n][k], At[m][k], acc[ai][bj][m][n], 0, 0, 0); __builtin_amdgcn_s_setprio(0); } while (0)
; #define PG8_WAIT_V(n) asm volatile("s_waitcnt vmcnt(" #n ")" ::: "memory")
; #define PG8_WAIT_L(n) asm volatile("s_waitcnt lgkmcnt(" #n ")" ::: "memory")
; #define PG8_BAR __builtin_amdgcn_s_barrier()
; #define PG8_SCHED __builtin_amdgcn_sched_barrier(0)
; template <class Epi, class Sched, bool ALIGN_EPI = false, bool SP2 = false>
; __device__ __forceinline__ void gemm_phase(PG8_LAS unsigned char* lds, const Gemm g, const Sched& S, const Epi& E) {
;     ...
;             PG8_WAIT_V(8); PG8_WAIT_L(0); PG8_BAR; PG8_MMA(1, 0, At, B0); PG8_MMA(1, 1, At, B1); PG8_BAR; PG8_SCHED;
;             PG8_LDB(B0, 1, 0); PG8_LDB(B1, 1, 1); PG8_SCHED; PG8_LDA(At, 1, 0); PG8_STAGE(PG8_SA(0, 1), a2 + hstep, voffA);
;             PG8_WAIT_V(8); PG8_WAIT_L(0); PG8_BAR; PG8_MMA(0, 0, At, B0); PG8_MMA(0, 1, At, B1); PG8_BAR; PG8_SCHED;
	s_waitcnt lgkmcnt(0)
	v_mfma_f32_16x16x32_bf16 v[60:63], v[64:67], v[172:175], 0
	v_mfma_f32_16x16x32_bf16 v[56:59], v[72:75], v[172:175], 0
	v_mfma_f32_16x16x32_bf16 v[52:55], v[64:67], v[180:183], 0
	v_mfma_f32_16x16x32_bf16 v[44:47], v[72:75], v[180:183], 0
	v_mfma_f32_16x16x32_bf16 v[28:31], v[64:67], v[188:191], 0
	v_mfma_f32_16x16x32_bf16 v[24:27], v[72:75], v[188:191], 0
	v_mfma_f32_16x16x32_bf16 v[12:15], v[64:67], v[196:199], 0
	v_mfma_f32_16x16x32_bf16 v[8:11], v[72:75], v[196:199], 0
	v_mfma_f32_16x16x32_bf16 v[60:63], v[68:71], v[176:179], v[60:63]
	v_mfma_f32_16x16x32_bf16 v[56:59], v[76:79], v[176:179], v[56:59]
	v_mfma_f32_16x16x32_bf16 v[52:55], v[68:71], v[184:187], v[52:55]
	v_mfma_f32_16x16x32_bf16 v[44:47], v[76:79], v[184:187], v[44:47]
	v_mfma_f32_16x16x32_bf16 v[28:31], v[68:71], v[192:195], v[28:31]
	v_mfma_f32_16x16x32_bf16 v[24:27], v[76:79], v[192:195], v[24:27]
	v_mfma_f32_16x16x32_bf16 v[12:15], v[68:71], v[200:203], v[12:15]
	v_mfma_f32_16x16x32_bf16 v[8:11], v[76:79], v[200:203], v[8:11]
	v_mfma_f32_16x16x32_bf16 v[48:51], v[156:159], v[172:175], 0
	v_mfma_f32_16x16x32_bf16 v[40:43], v[164:167], v[172:175], 0
	v_mfma_f32_16x16x32_bf16 v[36:39], v[156:159], v[180:183], 0
	v_mfma_f32_16x16x32_bf16 v[32:35], v[164:167], v[180:183], 0
	v_mfma_f32_16x16x32_bf16 v[20:23], v[156:159], v[188:191], 0
	v_mfma_f32_16x16x32_bf16 v[16:19], v[164:167], v[188:191], 0
	v_mfma_f32_16x16x32_bf16 v[4:7], v[156:159], v[196:199], 0
	v_mfma_f32_16x16x32_bf16 v[0:3], v[164:167], v[196:199], 0
	v_mfma_f32_16x16x32_bf16 v[48:51], v[160:163], v[176:179], v[48:51]
	v_mfma_f32_16x16x32_bf16 v[40:43], v[168:171], v[176:179], v[40:43]
	v_mfma_f32_16x16x32_bf16 v[36:39], v[160:163], v[184:187], v[36:39]
	v_mfma_f32_16x16x32_bf16 v[32:35], v[168:171], v[184:187], v[32:35]
	v_mfma_f32_16x16x32_bf16 v[20:23], v[160:163], v[192:195], v[20:23]
	v_mfma_f32_16x16x32_bf16 v[16:19], v[168:171], v[192:195], v[16:19]
	v_mfma_f32_16x16x32_bf16 v[4:7], v[160:163], v[200:203], v[4:7]
	v_mfma_f32_16x16x32_bf16 v[0:3], v[168:171], v[200:203], v[0:3]
	s_barrier
	s_add_i32 s84, 0, 0x18000
	s_add_i32 s85, 0, 0x1c000
	v_add_u32_e32 v76, s84, v228
	v_add_u32_e32 v168, s85, v228
	ds_read_b128 v[64:67], v76
	ds_read_b128 v[68:71], v76 offset:1024
	ds_read_b128 v[72:75], v76 offset:2048
	ds_read_b128 v[76:79], v76 offset:3072
	ds_read_b128 v[156:159], v168
	ds_read_b128 v[160:163], v168 offset:1024
	ds_read_b128 v[164:167], v168 offset:2048
	ds_read_b128 v[168:171], v168 offset:3072
	s_add_u32 s64, s64, 0x40000
	s_addc_u32 s65, s65, 0
	s_mov_b32 m0, s20
	v_lshl_add_u64 v[214:215], s[64:65], 0, v[150:151]
	ds_read_b128 v[172:175], v230 offset:32768
	ds_read_b128 v[176:179], v230 offset:33792
	ds_read_b128 v[180:183], v230 offset:34816
	ds_read_b128 v[184:187], v230 offset:35840
	ds_read_b128 v[188:191], v230 offset:36864
	ds_read_b128 v[192:195], v230 offset:37888
	ds_read_b128 v[196:199], v230 offset:38912
	ds_read_b128 v[200:203], v230 offset:39936
	global_load_lds_dwordx4 v[214:215], off
	v_lshl_add_u64 v[214:215], s[64:65], 0, v[148:149]
	s_mov_b32 m0, s21
	s_nop 0
	global_load_lds_dwordx4 v[214:215], off
	s_waitcnt vmcnt(8)
	s_waitcnt lgkmcnt(0)
	s_barrier
	s_waitcnt lgkmcnt(0)
	v_mfma_f32_16x16x32_bf16 v[142:145], v[64:67], v[172:175], v[142:145]
	v_mfma_f32_16x16x32_bf16 v[138:141], v[72:75], v[172:175], v[138:141]
	v_mfma_f32_16x16x32_bf16 v[134:137], v[64:67], v[180:183], v[134:137]
	v_mfma_f32_16x16x32_bf16 v[124:127], v[72:75], v[180:183], v[124:127]
	v_mfma_f32_16x16x32_bf16 v[108:111], v[64:67], v[188:191], v[108:111]
	v_mfma_f32_16x16x32_bf16 v[104:107], v[72:75], v[188:191], v[104:107]
	v_mfma_f32_16x16x32_bf16 v[100:103], v[64:67], v[196:199], v[100:103]
	v_mfma_f32_16x16x32_bf16 v[92:95], v[72:75], v[196:199], v[92:95]
	v_mfma_f32_16x16x32_bf16 v[142:145], v[68:71], v[176:179], v[142:145]
	v_mfma_f32_16x16x32_bf16 v[138:141], v[76:79], v[176:179], v[138:141]
	v_mfma_f32_16x16x32_bf16 v[134:137], v[68:71], v[184:187], v[134:137]
	v_mfma_f32_16x16x32_bf16 v[124:127], v[76:79], v[184:187], v[124:127]
	v_mfma_f32_16x16x32_bf16 v[108:111], v[68:71], v[192:195], v[108:111]
	v_mfma_f32_16x16x32_bf16 v[104:107], v[76:79], v[192:195], v[104:107]
	v_mfma_f32_16x16x32_bf16 v[100:103], v[68:71], v[200:203], v[100:103]
	v_mfma_f32_16x16x32_bf16 v[92:95], v[76:79], v[200:203], v[92:95]
	v_mfma_f32_16x16x32_bf16 v[130:133], v[156:159], v[172:175], v[130:133]
	v_mfma_f32_16x16x32_bf16 v[120:123], v[164:167], v[172:175], v[120:123]
	v_mfma_f32_16x16x32_bf16 v[116:119], v[156:159], v[180:183], v[116:119]
	v_mfma_f32_16x16x32_bf16 v[112:115], v[164:167], v[180:183], v[112:115]
	v_mfma_f32_16x16x32_bf16 v[96:99], v[156:159], v[188:191], v[96:99]
	v_mfma_f32_16x16x32_bf16 v[88:91], v[164:167], v[188:191], v[88:91]
	v_mfma_f32_16x16x32_bf16 v[84:87], v[156:159], v[196:199], v[84:87]
	v_mfma_f32_16x16x32_bf16 v[80:83], v[164:167], v[196:199], v[80:83]
	v_mfma_f32_16x16x32_bf16 v[130:133], v[160:163], v[176:179], v[130:133]
	v_mfma_f32_16x16x32_bf16 v[120:123], v[168:171], v[176:179], v[120:123]
	v_mfma_f32_16x16x32_bf16 v[116:119], v[160:163], v[184:187], v[116:119]
	v_mfma_f32_16x16x32_bf16 v[112:115], v[168:171], v[184:187], v[112:115]
	v_mfma_f32_16x16x32_bf16 v[96:99], v[160:163], v[192:195], v[96:99]
	v_mfma_f32_16x16x32_bf16 v[88:91], v[168:171], v[192:195], v[88:91]
	v_mfma_f32_16x16x32_bf16 v[84:87], v[160:163], v[200:203], v[84:87]
	v_mfma_f32_16x16x32_bf16 v[80:83], v[168:171], v[200:203], v[80:83]
	s_barrier
; #define PG8_STAGE(bufoff, gbase, voff) do { _Pragma("unroll") for (int _i = 0; _i < 2; ++_i) \
;         __builtin_amdgcn_global_load_lds((const unsigned*)((const char*)(gbase) + (voff)[_i]), (PG8_LAS unsigned*)(lds + (bufoff) + ldsw + _i * 8192), 16, 0, 0); } while (0)
; #define PG8_LDA(dst, b, h) do { _Pragma("unroll") for (int m = 0; m < 4; ++m) _Pragma("unroll") for (int k = 0; k < 2; ++k) dst[m][k] = *(const PG8_LAS bf16x8*)(lds + PG8_SA(b, h) + aoff + m * 2048 + k * 1024); } while (0)
; #define PG8_MMA(ai, bj, At, Bt) do { __builtin_amdgcn_s_setprio(1); _Pragma("unroll") for (int m = 0; m < 4; ++m) _Pragma("unroll") for (int n = 0; n < 2; ++n) _Pragma("unroll") for (int k = 0; k < 2; ++k) \
;         acc[ai][bj][m][n] = __builtin_amdgcn_mfma_f32_16x16x32_bf16(Bt[n][k], At[m][k], acc[ai][bj][m][n], 0, 0, 0); __builtin_amdgcn_s_setprio(0); } while (0)
; #define PG8_WAIT_V(n) asm volatile("s_waitcnt vmcnt(" #n ")" ::: "memory")
; #define PG8_WAIT_L(n) asm volatile("s_waitcnt lgkmcnt(" #n ")" ::: "memory")
; #define PG8_BAR __builtin_amdgcn_s_barrier()
; #define PG8_SCHED __builtin_amdgcn_sched_barrier(0)
; template <class Epi, class Sched, bool ALIGN_EPI = false, bool SP2 = false>
; __device__ __forceinline__ void gemm_phase(PG8_LAS unsigned char* lds, const Gemm g, const Sched& S, const Epi& E) {
;     ...
;         for (int t = 0; t < nt; t += 2) {
;             const bool last = (t == nt - 2);
;     ...
;             PG8_LDA(At, 1, 1); PG8_STAGE(PG8_SB(1, 0), b3, voffB); PG8_STAGE(PG8_SB(1, 1), b3 + hstep, voffB); PG8_STAGE(PG8_SA(1, 0), a3, voffA);
;             PG8_WAIT_V(8); PG8_WAIT_L(0); PG8_BAR; PG8_MMA(1, 0, At, B0); PG8_MMA(1, 1, At, B1); PG8_BAR; PG8_SCHED;
	s_add_i32 s64, s84, s17
	v_lshl_add_u64 v[204:205], v[204:205], 0, s[90:91]
	s_mov_b32 m0, s64
	ds_read_b128 v[172:175], v230 offset:49152
	ds_read_b128 v[176:179], v230 offset:50176
	ds_read_b128 v[180:183], v230 offset:51200
	ds_read_b128 v[184:187], v230 offset:52224
	ds_read_b128 v[188:191], v230 offset:53248
	ds_read_b128 v[192:195], v230 offset:54272
	ds_read_b128 v[196:199], v230 offset:55296
	ds_read_b128 v[200:203], v230 offset:56320
	global_load_lds_dwordx4 v[204:205], off
	s_add_i32 m0, s64, 0x2000
	s_add_u32 s58, s58, 0x40080
	v_lshl_add_u64 v[204:205], v[206:207], 0, s[90:91]
	s_addc_u32 s59, s59, 0
	s_add_i32 s64, s85, s17
	global_load_lds_dwordx4 v[204:205], off
	v_lshl_add_u64 v[204:205], s[58:59], 0, v[128:129]
	s_mov_b32 m0, s64
	s_nop 0
	global_load_lds_dwordx4 v[204:205], off
	v_lshl_add_u64 v[204:205], s[58:59], 0, v[146:147]
	s_add_i32 m0, s64, 0x2000
	s_nop 0
	global_load_lds_dwordx4 v[204:205], off
	v_lshl_add_u64 v[204:205], v[208:209], 0, s[90:91]
	s_mov_b32 m0, s28
	s_nop 0
	global_load_lds_dwordx4 v[204:205], off
	v_lshl_add_u64 v[204:205], v[210:211], 0, s[90:91]
	s_mov_b32 m0, s29
	s_nop 0
	global_load_lds_dwordx4 v[204:205], off
	s_waitcnt vmcnt(8)
	s_waitcnt lgkmcnt(0)
	s_barrier
	s_waitcnt lgkmcnt(0)
	v_mfma_f32_16x16x32_bf16 v[60:63], v[64:67], v[172:175], v[60:63]
	v_mfma_f32_16x16x32_bf16 v[56:59], v[72:75], v[172:175], v[56:59]
	v_mfma_f32_16x16x32_bf16 v[52:55], v[64:67], v[180:183], v[52:55]
	v_mfma_f32_16x16x32_bf16 v[44:47], v[72:75], v[180:183], v[44:47]
	v_mfma_f32_16x16x32_bf16 v[28:31], v[64:67], v[188:191], v[28:31]
	v_mfma_f32_16x16x32_bf16 v[24:27], v[72:75], v[188:191], v[24:27]
	v_mfma_f32_16x16x32_bf16 v[12:15], v[64:67], v[196:199], v[12:15]
	v_mfma_f32_16x16x32_bf16 v[8:11], v[72:75], v[196:199], v[8:11]
	v_mfma_f32_16x16x32_bf16 v[60:63], v[68:71], v[176:179], v[60:63]
	v_mfma_f32_16x16x32_bf16 v[56:59], v[76:79], v[176:179], v[56:59]
	v_mfma_f32_16x16x32_bf16 v[52:55], v[68:71], v[184:187], v[52:55]
	v_mfma_f32_16x16x32_bf16 v[44:47], v[76:79], v[184:187], v[44:47]
	v_mfma_f32_16x16x32_bf16 v[28:31], v[68:71], v[192:195], v[28:31]
	v_mfma_f32_16x16x32_bf16 v[24:27], v[76:79], v[192:195], v[24:27]
	v_mfma_f32_16x16x32_bf16 v[12:15], v[68:71], v[200:203], v[12:15]
	v_mfma_f32_16x16x32_bf16 v[8:11], v[76:79], v[200:203], v[8:11]
	v_mfma_f32_16x16x32_bf16 v[48:51], v[156:159], v[172:175], v[48:51]
	v_mfma_f32_16x16x32_bf16 v[40:43], v[164:167], v[172:175], v[40:43]
	v_mfma_f32_16x16x32_bf16 v[36:39], v[156:159], v[180:183], v[36:39]
	v_mfma_f32_16x16x32_bf16 v[32:35], v[164:167], v[180:183], v[32:35]
	v_mfma_f32_16x16x32_bf16 v[20:23], v[156:159], v[188:191], v[20:23]
	v_mfma_f32_16x16x32_bf16 v[16:19], v[164:167], v[188:191], v[16:19]
	v_mfma_f32_16x16x32_bf16 v[4:7], v[156:159], v[196:199], v[4:7]
	v_mfma_f32_16x16x32_bf16 v[0:3], v[164:167], v[196:199], v[0:3]
	v_mfma_f32_16x16x32_bf16 v[48:51], v[160:163], v[176:179], v[48:51]
	v_mfma_f32_16x16x32_bf16 v[40:43], v[168:171], v[176:179], v[40:43]
	v_mfma_f32_16x16x32_bf16 v[36:39], v[160:163], v[184:187], v[36:39]
	v_mfma_f32_16x16x32_bf16 v[32:35], v[168:171], v[184:187], v[32:35]
	v_mfma_f32_16x16x32_bf16 v[20:23], v[160:163], v[192:195], v[20:23]
	v_mfma_f32_16x16x32_bf16 v[16:19], v[168:171], v[192:195], v[16:19]
	v_mfma_f32_16x16x32_bf16 v[4:7], v[160:163], v[200:203], v[4:7]
	v_mfma_f32_16x16x32_bf16 v[0:3], v[168:171], v[200:203], v[0:3]
	s_barrier
	s_add_i32 s94, s94, 2
	s_add_u32 vcc_lo, vcc_lo, 0x100
	s_addc_u32 vcc_hi, vcc_hi, 0
	s_add_u32 s88, s88, 0x100
	s_addc_u32 s93, s93, 0
	s_cmp_gt_u32 s94, 13
	s_cbranch_scc1 .Lpeel_x3

; #define PG8_BAR __builtin_amdgcn_s_barrier()
; template <class Epi, class Sched, bool ALIGN_EPI = false, bool SP2 = false>
; __device__ __forceinline__ void gemm_phase(PG8_LAS unsigned char* lds, const Gemm g, const Sched& S, const Epi& E) {
;     ...
;         if constexpr (ALIGN_EPI) { if (wr == 0) PG8_BAR; }
.Lpeel_x3:
	s_setprio 0
	s_and_b64 vcc, exec, s[72:73]
	s_cbranch_vccz .LBB0_601
	s_barrier

; #define PG8_STAGE(bufoff, gbase, voff) do { _Pragma("unroll") for (int _i = 0; _i < 2; ++_i) \
;         __builtin_amdgcn_global_load_lds((const unsigned*)((const char*)(gbase) + (voff)[_i]), (PG8_LAS unsigned*)(lds + (bufoff) + ldsw + _i * 8192), 16, 0, 0); } while (0)
; #define PG8_LDA(dst, b, h) do { _Pragma("unroll") for (int m = 0; m < 4; ++m) _Pragma("unroll") for (int k = 0; k < 2; ++k) dst[m][k] = *(const PG8_LAS bf16x8*)(lds + PG8_SA(b, h) + aoff + m * 2048 + k * 1024); } while (0)
; #define PG8_LDB(dst, b, h) do { _Pragma("unroll") for (int n = 0; n < 2; ++n) _Pragma("unroll") for (int k = 0; k < 2; ++k) dst[n][k] = *(const PG8_LAS bf16x8*)(lds + PG8_SB(b, h) + boff + n * 2048 + k * 1024); } while (0)
; #define PG8_MMA(ai, bj, At, Bt) do { __builtin_amdgcn_s_setprio(1); _Pragma("unroll") for (int m = 0; m < 4; ++m) _Pragma("unroll") for (int n = 0; n < 2; ++n) _Pragma("unroll") for (int k = 0; k < 2; ++k) \
;         acc[ai][bj][m][n] = __builtin_amdgcn_mfma_f32_16x16x32_bf16(Bt[n][k], At[m][k], acc[ai][bj][m][n], 0, 0, 0); __builtin_amdgcn_s_setprio(0); } while (0)
; #define PG8_BAR __builtin_amdgcn_s_barrier()
; template <class Epi, class Sched, bool ALIGN_EPI = false, bool SP2 = false>
; __device__ __forceinline__ void gemm_phase(PG8_LAS unsigned char* lds, const Gemm g, const Sched& S, const Epi& E) {
;     ...
;         const bool has_next = S.next(ui + 1, nxt);
;         const char* nA = has_next ? (const char*)g.A + (size_t)nxt.pm * tstep : cA; const char* nB = has_next ? (const char*)g.Bt + (size_t)nxt.pn * tstep : cB;
;         for (int t = 0; t < nt; t += 2) {
;             const bool last = (t == nt - 2);
;             const char* a1 = cA + (size_t)(t + 1) * kstep;
;             const char* a2 = last ? nA : cA + (size_t)(t + 2) * kstep; const char* b2 = last ? nB : cB + (size_t)(t + 2) * kstep;
;             const char* a3 = a2 + kstep; const char* b3 = b2 + kstep;
;             if (last && has_next) S.a_ready(nxt);
;             if constexpr (SP2) {
;             PG8_LDB(B0, 0, 0); PG8_LDB(B1, 0, 1); PG8_SCHED; PG8_LDA(At, 0, 0); PG8_STAGE(PG8_SA(1, 1), a1 + hstep, voffA);
;             PG8_WAIT_V(8); PG8_WAIT_L(0); PG8_BAR; PG8_MMA(0, 0, At, B0); PG8_MMA(0, 1, At, B1); PG8_BAR; PG8_SCHED;
;             PG8_LDA(At, 0, 1); PG8_STAGE(PG8_SB(0, 0), b2, voffB); PG8_STAGE(PG8_SB(0, 1), b2 + hstep, voffB); PG8_STAGE(PG8_SA(0, 0), a2, voffA);
.LBB0_812:
	s_ashr_i32 s49, s48, 31
	s_lshl_b64 s[28:29], s[48:49], 19
	s_add_u32 s52, s2, s28
	s_addc_u32 s53, s14, s29
	s_and_b64 s[28:29], s[38:39], exec
	s_cselect_b32 s28, s53, s65
	s_cselect_b32 s29, s52, s64
	s_ashr_i32 s51, s50, 31
	s_lshl_b64 s[30:31], s[50:51], 19
	s_add_u32 s62, s15, s30
	s_addc_u32 s63, s16, s31
	s_and_b64 s[30:31], s[38:39], exec
	s_cselect_b32 s30, s63, s59
	s_cselect_b32 s31, s62, s58
	s_add_u32 s66, s64, 0x40080
	s_addc_u32 s67, s65, 0
	s_add_u32 s34, s58, 0x100
	s_addc_u32 s35, s59, 0
	s_mov_b32 s36, -2
	s_and_b64 s[98:99], exec, s[46:47]
	s_cbranch_scc1 .Lsp_0
	s_setprio 1
.Lsp_0:
	s_add_u32 s8, s66, 0xfffc0080
	s_addc_u32 s37, s67, -1
	s_add_i32 s49, 0, 0x10000
	s_cmp_eq_u32 s36, 12
	s_cselect_b32 s65, s28, s37
	s_cselect_b32 s64, s29, s8
	s_cselect_b32 s59, s30, s35
	s_cselect_b32 s58, s31, s34
	s_add_i32 s8, 0, 0x14000
	v_add_u32_e32 v156, s49, v145
	v_add_u32_e32 v172, s8, v145
	ds_read_b128 v[140:143], v156
	ds_read_b128 v[148:151], v156 offset:1024
	ds_read_b128 v[152:155], v156 offset:2048
	ds_read_b128 v[156:159], v156 offset:3072
	ds_read_b128 v[160:163], v172
	ds_read_b128 v[164:167], v172 offset:1024
	ds_read_b128 v[168:171], v172 offset:2048
	ds_read_b128 v[172:175], v172 offset:3072
	v_lshl_add_u64 v[208:209], s[66:67], 0, v[136:137]
	s_add_i32 m0, s18, 0xc000
	ds_read_b128 v[176:179], v147
	ds_read_b128 v[180:183], v147 offset:1024
	ds_read_b128 v[184:187], v147 offset:2048
	ds_read_b128 v[188:191], v147 offset:3072
	ds_read_b128 v[192:195], v147 offset:4096
	ds_read_b128 v[196:199], v147 offset:5120
	ds_read_b128 v[200:203], v147 offset:6144
	ds_read_b128 v[204:207], v147 offset:7168
	global_load_lds_dwordx4 v[208:209], off
	v_lshl_add_u64 v[208:209], s[66:67], 0, v[138:139]
	s_add_i32 m0, s18, 0xe000
	s_nop 0
	global_load_lds_dwordx4 v[208:209], off
	s_waitcnt vmcnt(8)
	s_waitcnt lgkmcnt(0)
	s_barrier
	s_waitcnt lgkmcnt(0)
	v_mfma_f32_16x16x32_bf16 v[124:127], v[140:143], v[176:179], 0
	v_mfma_f32_16x16x32_bf16 v[116:119], v[152:155], v[176:179], 0
	v_mfma_f32_16x16x32_bf16 v[108:111], v[140:143], v[184:187], 0
	v_mfma_f32_16x16x32_bf16 v[100:103], v[152:155], v[184:187], 0
	v_mfma_f32_16x16x32_bf16 v[92:95], v[140:143], v[192:195], 0
	v_mfma_f32_16x16x32_bf16 v[84:87], v[152:155], v[192:195], 0
	v_mfma_f32_16x16x32_bf16 v[76:79], v[140:143], v[200:203], 0
	v_mfma_f32_16x16x32_bf16 v[68:71], v[152:155], v[200:203], 0
	v_mfma_f32_16x16x32_bf16 v[124:127], v[148:151], v[180:183], v[124:127]
	v_mfma_f32_16x16x32_bf16 v[116:119], v[156:159], v[180:183], v[116:119]
	v_mfma_f32_16x16x32_bf16 v[108:111], v[148:151], v[188:191], v[108:111]
	v_mfma_f32_16x16x32_bf16 v[100:103], v[156:159], v[188:191], v[100:103]
	v_mfma_f32_16x16x32_bf16 v[92:95], v[148:151], v[196:199], v[92:95]
	v_mfma_f32_16x16x32_bf16 v[84:87], v[156:159], v[196:199], v[84:87]
	v_mfma_f32_16x16x32_bf16 v[76:79], v[148:151], v[204:207], v[76:79]
	v_mfma_f32_16x16x32_bf16 v[68:71], v[156:159], v[204:207], v[68:71]
	v_mfma_f32_16x16x32_bf16 v[120:123], v[160:163], v[176:179], 0
	v_mfma_f32_16x16x32_bf16 v[112:115], v[168:171], v[176:179], 0
	v_mfma_f32_16x16x32_bf16 v[104:107], v[160:163], v[184:187], 0
	v_mfma_f32_16x16x32_bf16 v[96:99], v[168:171], v[184:187], 0
	v_mfma_f32_16x16x32_bf16 v[88:91], v[160:163], v[192:195], 0
	v_mfma_f32_16x16x32_bf16 v[80:83], v[168:171], v[192:195], 0
	v_mfma_f32_16x16x32_bf16 v[72:75], v[160:163], v[200:203], 0
	v_mfma_f32_16x16x32_bf16 v[64:67], v[168:171], v[200:203], 0
	v_mfma_f32_16x16x32_bf16 v[120:123], v[164:167], v[180:183], v[120:123]
	v_mfma_f32_16x16x32_bf16 v[112:115], v[172:175], v[180:183], v[112:115]
	v_mfma_f32_16x16x32_bf16 v[104:107], v[164:167], v[188:191], v[104:107]
	v_mfma_f32_16x16x32_bf16 v[96:99], v[172:175], v[188:191], v[96:99]
	v_mfma_f32_16x16x32_bf16 v[88:91], v[164:167], v[196:199], v[88:91]
	v_mfma_f32_16x16x32_bf16 v[80:83], v[172:175], v[196:199], v[80:83]
	v_mfma_f32_16x16x32_bf16 v[72:75], v[164:167], v[204:207], v[72:75]
	v_mfma_f32_16x16x32_bf16 v[64:67], v[172:175], v[204:207], v[64:67]
	s_barrier
	s_add_i32 s37, s49, s17
	v_lshl_add_u64 v[208:209], s[58:59], 0, v[128:129]
	s_mov_b32 m0, s37
	ds_read_b128 v[176:179], v147 offset:16384
	ds_read_b128 v[180:183], v147 offset:17408
	ds_read_b128 v[184:187], v147 offset:18432
	ds_read_b128 v[188:191], v147 offset:19456
	ds_read_b128 v[192:195], v147 offset:20480
	ds_read_b128 v[196:199], v147 offset:21504
	ds_read_b128 v[200:203], v147 offset:22528
	ds_read_b128 v[204:207], v147 offset:23552
	global_load_lds_dwordx4 v[208:209], off
	s_add_i32 m0, s37, 0x2000
	s_add_u32 s72, s58, 0x40000
	v_lshl_add_u64 v[210:211], s[58:59], 0, v[130:131]
	s_addc_u32 s73, s59, 0
	s_add_i32 s8, s8, s17
	global_load_lds_dwordx4 v[210:211], off
	v_lshl_add_u64 v[214:215], s[72:73], 0, v[128:129]
	s_mov_b32 m0, s8
	v_lshl_add_u64 v[222:223], s[64:65], 0, v[132:133]
	global_load_lds_dwordx4 v[214:215], off
	v_lshl_add_u64 v[214:215], s[72:73], 0, v[130:131]
	s_add_i32 m0, s8, 0x2000
	s_nop 0
	global_load_lds_dwordx4 v[214:215], off
	v_lshl_add_u64 v[214:215], s[64:65], 0, v[134:135]
	s_mov_b32 m0, s18
	s_nop 0
	global_load_lds_dwordx4 v[214:215], off
	s_mov_b32 m0, s19
	s_nop 0
	global_load_lds_dwordx4 v[222:223], off
	s_waitcnt vmcnt(8)
	s_waitcnt lgkmcnt(0)
	s_barrier
; #define PG8_STAGE(bufoff, gbase, voff) do { _Pragma("unroll") for (int _i = 0; _i < 2; ++_i) \
;         __builtin_amdgcn_global_load_lds((const unsigned*)((const char*)(gbase) + (voff)[_i]), (PG8_LAS unsigned*)(lds + (bufoff) + ldsw + _i * 8192), 16, 0, 0); } while (0)
; #define PG8_LDA(dst, b, h) do { _Pragma("unroll") for (int m = 0; m < 4; ++m) _Pragma("unroll") for (int k = 0; k < 2; ++k) dst[m][k] = *(const PG8_LAS bf16x8*)(lds + PG8_SA(b, h) + aoff + m * 2048 + k * 1024); } while (0)
; #define PG8_LDB(dst, b, h) do { _Pragma("unroll") for (int n = 0; n < 2; ++n) _Pragma("unroll") for (int k = 0; k < 2; ++k) dst[n][k] = *(const PG8_LAS bf16x8*)(lds + PG8_SB(b, h) + boff + n * 2048 + k * 1024); } while (0)
; #define PG8_MMA(ai, bj, At, Bt) do { __builtin_amdgcn_s_setprio(1); _Pragma("unroll") for (int m = 0; m < 4; ++m) _Pragma("unroll") for (int n = 0; n < 2; ++n) _Pragma("unroll") for (int k = 0; k < 2; ++k) \
;         acc[ai][bj][m][n] = __builtin_amdgcn_mfma_f32_16x16x32_bf16(Bt[n][k], At[m][k], acc[ai][bj][m][n], 0, 0, 0); __builtin_amdgcn_s_setprio(0); } while (0)
; #define PG8_WAIT_V(n) asm volatile("s_waitcnt vmcnt(" #n ")" ::: "memory")
; #define PG8_WAIT_L(n) asm volatile("s_waitcnt lgkmcnt(" #n ")" ::: "memory")
; #define PG8_BAR __builtin_amdgcn_s_barrier()
; #define PG8_SCHED __builtin_amdgcn_sched_barrier(0)
; template <class Epi, class Sched, bool ALIGN_EPI = false, bool SP2 = false>
; __device__ __forceinline__ void gemm_phase(PG8_LAS unsigned char* lds, const Gemm g, const Sched& S, const Epi& E) {
;     ...
;             PG8_WAIT_V(8); PG8_WAIT_L(0); PG8_BAR; PG8_MMA(1, 0, At, B0); PG8_MMA(1, 1, At, B1); PG8_BAR; PG8_SCHED;
;             PG8_LDB(B0, 1, 0); PG8_LDB(B1, 1, 1); PG8_SCHED; PG8_LDA(At, 1, 0); PG8_STAGE(PG8_SA(0, 1), a2 + hstep, voffA);
;             PG8_WAIT_V(8); PG8_WAIT_L(0); PG8_BAR; PG8_MMA(0, 0, At, B0); PG8_MMA(0, 1, At, B1); PG8_BAR; PG8_SCHED;
	s_waitcnt lgkmcnt(0)
	v_mfma_f32_16x16x32_bf16 v[60:63], v[140:143], v[176:179], 0
	v_mfma_f32_16x16x32_bf16 v[52:55], v[152:155], v[176:179], 0
	v_mfma_f32_16x16x32_bf16 v[44:47], v[140:143], v[184:187], 0
	v_mfma_f32_16x16x32_bf16 v[36:39], v[152:155], v[184:187], 0
	v_mfma_f32_16x16x32_bf16 v[28:31], v[140:143], v[192:195], 0
	v_mfma_f32_16x16x32_bf16 v[20:23], v[152:155], v[192:195], 0
	v_mfma_f32_16x16x32_bf16 v[12:15], v[140:143], v[200:203], 0
	v_mfma_f32_16x16x32_bf16 v[4:7], v[152:155], v[200:203], 0
	v_mfma_f32_16x16x32_bf16 v[60:63], v[148:151], v[180:183], v[60:63]
	v_mfma_f32_16x16x32_bf16 v[52:55], v[156:159], v[180:183], v[52:55]
	v_mfma_f32_16x16x32_bf16 v[44:47], v[148:151], v[188:191], v[44:47]
	v_mfma_f32_16x16x32_bf16 v[36:39], v[156:159], v[188:191], v[36:39]
	v_mfma_f32_16x16x32_bf16 v[28:31], v[148:151], v[196:199], v[28:31]
	v_mfma_f32_16x16x32_bf16 v[20:23], v[156:159], v[196:199], v[20:23]
	v_mfma_f32_16x16x32_bf16 v[12:15], v[148:151], v[204:207], v[12:15]
	v_mfma_f32_16x16x32_bf16 v[4:7], v[156:159], v[204:207], v[4:7]
	v_mfma_f32_16x16x32_bf16 v[56:59], v[160:163], v[176:179], 0
	v_mfma_f32_16x16x32_bf16 v[48:51], v[168:171], v[176:179], 0
	v_mfma_f32_16x16x32_bf16 v[40:43], v[160:163], v[184:187], 0
	v_mfma_f32_16x16x32_bf16 v[32:35], v[168:171], v[184:187], 0
	v_mfma_f32_16x16x32_bf16 v[24:27], v[160:163], v[192:195], 0
	v_mfma_f32_16x16x32_bf16 v[16:19], v[168:171], v[192:195], 0
	v_mfma_f32_16x16x32_bf16 v[8:11], v[160:163], v[200:203], 0
	v_mfma_f32_16x16x32_bf16 v[0:3], v[168:171], v[200:203], 0
	v_mfma_f32_16x16x32_bf16 v[56:59], v[164:167], v[180:183], v[56:59]
	v_mfma_f32_16x16x32_bf16 v[48:51], v[172:175], v[180:183], v[48:51]
	v_mfma_f32_16x16x32_bf16 v[40:43], v[164:167], v[188:191], v[40:43]
	v_mfma_f32_16x16x32_bf16 v[32:35], v[172:175], v[188:191], v[32:35]
	v_mfma_f32_16x16x32_bf16 v[24:27], v[164:167], v[196:199], v[24:27]
	v_mfma_f32_16x16x32_bf16 v[16:19], v[172:175], v[196:199], v[16:19]
	v_mfma_f32_16x16x32_bf16 v[8:11], v[164:167], v[204:207], v[8:11]
	v_mfma_f32_16x16x32_bf16 v[0:3], v[172:175], v[204:207], v[0:3]
	s_barrier
	s_add_i32 s8, 0, 0x18000
	s_add_i32 s37, 0, 0x1c000
	v_add_u32_e32 v156, s8, v145
	v_add_u32_e32 v172, s37, v145
	ds_read_b128 v[140:143], v156
	ds_read_b128 v[148:151], v156 offset:1024
	ds_read_b128 v[152:155], v156 offset:2048
	ds_read_b128 v[156:159], v156 offset:3072
	ds_read_b128 v[160:163], v172
	ds_read_b128 v[164:167], v172 offset:1024
	ds_read_b128 v[168:171], v172 offset:2048
	ds_read_b128 v[172:175], v172 offset:3072
	s_add_u32 s64, s64, 0x40000
	s_addc_u32 s65, s65, 0
	s_mov_b32 m0, s20
	v_lshl_add_u64 v[228:229], s[64:65], 0, v[134:135]
	ds_read_b128 v[176:179], v147 offset:32768
	ds_read_b128 v[180:183], v147 offset:33792
	ds_read_b128 v[184:187], v147 offset:34816
	ds_read_b128 v[188:191], v147 offset:35840
	ds_read_b128 v[192:195], v147 offset:36864
	ds_read_b128 v[196:199], v147 offset:37888
	ds_read_b128 v[200:203], v147 offset:38912
	ds_read_b128 v[204:207], v147 offset:39936
	global_load_lds_dwordx4 v[228:229], off
	v_lshl_add_u64 v[228:229], s[64:65], 0, v[132:133]
	s_mov_b32 m0, s21
	s_nop 0
	global_load_lds_dwordx4 v[228:229], off
	s_waitcnt vmcnt(8)
	s_waitcnt lgkmcnt(0)
	s_barrier
	s_waitcnt lgkmcnt(0)
	v_mfma_f32_16x16x32_bf16 v[124:127], v[140:143], v[176:179], v[124:127]
	v_mfma_f32_16x16x32_bf16 v[116:119], v[152:155], v[176:179], v[116:119]
	v_mfma_f32_16x16x32_bf16 v[108:111], v[140:143], v[184:187], v[108:111]
	v_mfma_f32_16x16x32_bf16 v[100:103], v[152:155], v[184:187], v[100:103]
	v_mfma_f32_16x16x32_bf16 v[92:95], v[140:143], v[192:195], v[92:95]
	v_mfma_f32_16x16x32_bf16 v[84:87], v[152:155], v[192:195], v[84:87]
	v_mfma_f32_16x16x32_bf16 v[76:79], v[140:143], v[200:203], v[76:79]
	v_mfma_f32_16x16x32_bf16 v[68:71], v[152:155], v[200:203], v[68:71]
	v_mfma_f32_16x16x32_bf16 v[124:127], v[148:151], v[180:183], v[124:127]
	v_mfma_f32_16x16x32_bf16 v[116:119], v[156:159], v[180:183], v[116:119]
	v_mfma_f32_16x16x32_bf16 v[108:111], v[148:151], v[188:191], v[108:111]
	v_mfma_f32_16x16x32_bf16 v[100:103], v[156:159], v[188:191], v[100:103]
	v_mfma_f32_16x16x32_bf16 v[92:95], v[148:151], v[196:199], v[92:95]
	v_mfma_f32_16x16x32_bf16 v[84:87], v[156:159], v[196:199], v[84:87]
	v_mfma_f32_16x16x32_bf16 v[76:79], v[148:151], v[204:207], v[76:79]
	v_mfma_f32_16x16x32_bf16 v[68:71], v[156:159], v[204:207], v[68:71]
	v_mfma_f32_16x16x32_bf16 v[120:123], v[160:163], v[176:179], v[120:123]
	v_mfma_f32_16x16x32_bf16 v[112:115], v[168:171], v[176:179], v[112:115]
	v_mfma_f32_16x16x32_bf16 v[104:107], v[160:163], v[184:187], v[104:107]
	v_mfma_f32_16x16x32_bf16 v[96:99], v[168:171], v[184:187], v[96:99]
	v_mfma_f32_16x16x32_bf16 v[88:91], v[160:163], v[192:195], v[88:91]
	v_mfma_f32_16x16x32_bf16 v[80:83], v[168:171], v[192:195], v[80:83]
	v_mfma_f32_16x16x32_bf16 v[72:75], v[160:163], v[200:203], v[72:75]
	v_mfma_f32_16x16x32_bf16 v[64:67], v[168:171], v[200:203], v[64:67]
	v_mfma_f32_16x16x32_bf16 v[120:123], v[164:167], v[180:183], v[120:123]
	v_mfma_f32_16x16x32_bf16 v[112:115], v[172:175], v[180:183], v[112:115]
	v_mfma_f32_16x16x32_bf16 v[104:107], v[164:167], v[188:191], v[104:107]
	v_mfma_f32_16x16x32_bf16 v[96:99], v[172:175], v[188:191], v[96:99]
	v_mfma_f32_16x16x32_bf16 v[88:91], v[164:167], v[196:199], v[88:91]
	v_mfma_f32_16x16x32_bf16 v[80:83], v[172:175], v[196:199], v[80:83]
	v_mfma_f32_16x16x32_bf16 v[72:75], v[164:167], v[204:207], v[72:75]
	v_mfma_f32_16x16x32_bf16 v[64:67], v[172:175], v[204:207], v[64:67]
	s_barrier
; #define PG8_STAGE(bufoff, gbase, voff) do { _Pragma("unroll") for (int _i = 0; _i < 2; ++_i) \
;         __builtin_amdgcn_global_load_lds((const unsigned*)((const char*)(gbase) + (voff)[_i]), (PG8_LAS unsigned*)(lds + (bufoff) + ldsw + _i * 8192), 16, 0, 0); } while (0)
; #define PG8_LDA(dst, b, h) do { _Pragma("unroll") for (int m = 0; m < 4; ++m) _Pragma("unroll") for (int k = 0; k < 2; ++k) dst[m][k] = *(const PG8_LAS bf16x8*)(lds + PG8_SA(b, h) + aoff + m * 2048 + k * 1024); } while (0)
; #define PG8_MMA(ai, bj, At, Bt) do { __builtin_amdgcn_s_setprio(1); _Pragma("unroll") for (int m = 0; m < 4; ++m) _Pragma("unroll") for (int n = 0; n < 2; ++n) _Pragma("unroll") for (int k = 0; k < 2; ++k) \
;         acc[ai][bj][m][n] = __builtin_amdgcn_mfma_f32_16x16x32_bf16(Bt[n][k], At[m][k], acc[ai][bj][m][n], 0, 0, 0); __builtin_amdgcn_s_setprio(0); } while (0)
; #define PG8_WAIT_V(n) asm volatile("s_waitcnt vmcnt(" #n ")" ::: "memory")
; #define PG8_WAIT_L(n) asm volatile("s_waitcnt lgkmcnt(" #n ")" ::: "memory")
; #define PG8_BAR __builtin_amdgcn_s_barrier()
; #define PG8_SCHED __builtin_amdgcn_sched_barrier(0)
; template <class Epi, class Sched, bool ALIGN_EPI = false, bool SP2 = false>
; __device__ __forceinline__ void gemm_phase(PG8_LAS unsigned char* lds, const Gemm g, const Sched& S, const Epi& E) {
;     ...
;         for (int t = 0; t < nt; t += 2) {
;             const bool last = (t == nt - 2);
;     ...
;             PG8_LDA(At, 1, 1); PG8_STAGE(PG8_SB(1, 0), b3, voffB); PG8_STAGE(PG8_SB(1, 1), b3 + hstep, voffB); PG8_STAGE(PG8_SA(1, 0), a3, voffA);
;             PG8_WAIT_V(8); PG8_WAIT_L(0); PG8_BAR; PG8_MMA(1, 0, At, B0); PG8_MMA(1, 1, At, B1); PG8_BAR; PG8_SCHED;
	s_add_i32 s8, s8, s17
	v_lshl_add_u64 v[208:209], v[208:209], 0, s[90:91]
	s_mov_b32 m0, s8
	ds_read_b128 v[176:179], v147 offset:49152
	ds_read_b128 v[180:183], v147 offset:50176
	ds_read_b128 v[184:187], v147 offset:51200
	ds_read_b128 v[188:191], v147 offset:52224
	ds_read_b128 v[192:195], v147 offset:53248
	ds_read_b128 v[196:199], v147 offset:54272
	ds_read_b128 v[200:203], v147 offset:55296
	ds_read_b128 v[204:207], v147 offset:56320
	global_load_lds_dwordx4 v[208:209], off
	s_add_i32 m0, s8, 0x2000
	s_add_u32 s58, s58, 0x40080
	v_lshl_add_u64 v[208:209], v[210:211], 0, s[90:91]
	s_addc_u32 s59, s59, 0
	s_add_i32 s8, s37, s17
	global_load_lds_dwordx4 v[208:209], off
	v_lshl_add_u64 v[208:209], s[58:59], 0, v[128:129]
	s_mov_b32 m0, s8
	s_nop 0
	global_load_lds_dwordx4 v[208:209], off
	v_lshl_add_u64 v[208:209], s[58:59], 0, v[130:131]
	s_add_i32 m0, s8, 0x2000
	s_nop 0
	global_load_lds_dwordx4 v[208:209], off
	v_lshl_add_u64 v[208:209], v[214:215], 0, s[90:91]
	s_mov_b32 m0, s22
	s_nop 0
	global_load_lds_dwordx4 v[208:209], off
	v_lshl_add_u64 v[208:209], v[222:223], 0, s[90:91]
	s_mov_b32 m0, s23
	s_nop 0
	global_load_lds_dwordx4 v[208:209], off
	s_waitcnt vmcnt(8)
	s_waitcnt lgkmcnt(0)
	s_barrier
	s_waitcnt lgkmcnt(0)
	v_mfma_f32_16x16x32_bf16 v[60:63], v[140:143], v[176:179], v[60:63]
	v_mfma_f32_16x16x32_bf16 v[52:55], v[152:155], v[176:179], v[52:55]
	v_mfma_f32_16x16x32_bf16 v[44:47], v[140:143], v[184:187], v[44:47]
	v_mfma_f32_16x16x32_bf16 v[36:39], v[152:155], v[184:187], v[36:39]
	v_mfma_f32_16x16x32_bf16 v[28:31], v[140:143], v[192:195], v[28:31]
	v_mfma_f32_16x16x32_bf16 v[20:23], v[152:155], v[192:195], v[20:23]
	v_mfma_f32_16x16x32_bf16 v[12:15], v[140:143], v[200:203], v[12:15]
	v_mfma_f32_16x16x32_bf16 v[4:7], v[152:155], v[200:203], v[4:7]
	v_mfma_f32_16x16x32_bf16 v[60:63], v[148:151], v[180:183], v[60:63]
	v_mfma_f32_16x16x32_bf16 v[52:55], v[156:159], v[180:183], v[52:55]
	v_mfma_f32_16x16x32_bf16 v[44:47], v[148:151], v[188:191], v[44:47]
	v_mfma_f32_16x16x32_bf16 v[36:39], v[156:159], v[188:191], v[36:39]
	v_mfma_f32_16x16x32_bf16 v[28:31], v[148:151], v[196:199], v[28:31]
	v_mfma_f32_16x16x32_bf16 v[20:23], v[156:159], v[196:199], v[20:23]
	v_mfma_f32_16x16x32_bf16 v[12:15], v[148:151], v[204:207], v[12:15]
	v_mfma_f32_16x16x32_bf16 v[4:7], v[156:159], v[204:207], v[4:7]
	v_mfma_f32_16x16x32_bf16 v[56:59], v[160:163], v[176:179], v[56:59]
	v_mfma_f32_16x16x32_bf16 v[48:51], v[168:171], v[176:179], v[48:51]
	v_mfma_f32_16x16x32_bf16 v[40:43], v[160:163], v[184:187], v[40:43]
	v_mfma_f32_16x16x32_bf16 v[32:35], v[168:171], v[184:187], v[32:35]
	v_mfma_f32_16x16x32_bf16 v[24:27], v[160:163], v[192:195], v[24:27]
	v_mfma_f32_16x16x32_bf16 v[16:19], v[168:171], v[192:195], v[16:19]
	v_mfma_f32_16x16x32_bf16 v[8:11], v[160:163], v[200:203], v[8:11]
	v_mfma_f32_16x16x32_bf16 v[0:3], v[168:171], v[200:203], v[0:3]
	v_mfma_f32_16x16x32_bf16 v[56:59], v[164:167], v[180:183], v[56:59]
	v_mfma_f32_16x16x32_bf16 v[48:51], v[172:175], v[180:183], v[48:51]
	v_mfma_f32_16x16x32_bf16 v[40:43], v[164:167], v[188:191], v[40:43]
	v_mfma_f32_16x16x32_bf16 v[32:35], v[172:175], v[188:191], v[32:35]
	v_mfma_f32_16x16x32_bf16 v[24:27], v[164:167], v[196:199], v[24:27]
	v_mfma_f32_16x16x32_bf16 v[16:19], v[172:175], v[196:199], v[16:19]
	v_mfma_f32_16x16x32_bf16 v[8:11], v[164:167], v[204:207], v[8:11]
	v_mfma_f32_16x16x32_bf16 v[0:3], v[172:175], v[204:207], v[0:3]
	s_barrier
	s_add_i32 s36, s36, 2
	s_add_u32 s66, s66, 0x100
	s_addc_u32 s67, s67, 0
	s_add_u32 s34, s34, 0x100
	s_addc_u32 s35, s35, 0
	s_cmp_gt_u32 s36, 13
	s_cbranch_scc1 .Lpeel_x0

; #define PG8_BAR __builtin_amdgcn_s_barrier()
; template <class Epi, class Sched, bool ALIGN_EPI = false, bool SP2 = false>
; __device__ __forceinline__ void gemm_phase(PG8_LAS unsigned char* lds, const Gemm g, const Sched& S, const Epi& E) {
;     ...
;         if constexpr (ALIGN_EPI) { if (wr == 0) PG8_BAR; }
.Lpeel_x0:
	s_setprio 0
	s_and_b64 vcc, exec, s[46:47]
	s_cbranch_vccz .LBB0_816
	s_barrier

; #define PG8_STAGE(bufoff, gbase, voff) do { _Pragma("unroll") for (int _i = 0; _i < 2; ++_i) \
;         __builtin_amdgcn_global_load_lds((const unsigned*)((const char*)(gbase) + (voff)[_i]), (PG8_LAS unsigned*)(lds + (bufoff) + ldsw + _i * 8192), 16, 0, 0); } while (0)
; #define PG8_LDA(dst, b, h) do { _Pragma("unroll") for (int m = 0; m < 4; ++m) _Pragma("unroll") for (int k = 0; k < 2; ++k) dst[m][k] = *(const PG8_LAS bf16x8*)(lds + PG8_SA(b, h) + aoff + m * 2048 + k * 1024); } while (0)
; #define PG8_LDB(dst, b, h) do { _Pragma("unroll") for (int n = 0; n < 2; ++n) _Pragma("unroll") for (int k = 0; k < 2; ++k) dst[n][k] = *(const PG8_LAS bf16x8*)(lds + PG8_SB(b, h) + boff + n * 2048 + k * 1024); } while (0)
; #define PG8_MMA(ai, bj, At, Bt) do { __builtin_amdgcn_s_setprio(1); _Pragma("unroll") for (int m = 0; m < 4; ++m) _Pragma("unroll") for (int n = 0; n < 2; ++n) _Pragma("unroll") for (int k = 0; k < 2; ++k) \
;         acc[ai][bj][m][n] = __builtin_amdgcn_mfma_f32_16x16x32_bf16(Bt[n][k], At[m][k], acc[ai][bj][m][n], 0, 0, 0); __builtin_amdgcn_s_setprio(0); } while (0)
; #define PG8_BAR __builtin_amdgcn_s_barrier()
; template <class Epi, class Sched, bool ALIGN_EPI = false, bool SP2 = false>
; __device__ __forceinline__ void gemm_phase(PG8_LAS unsigned char* lds, const Gemm g, const Sched& S, const Epi& E) {
;     ...
;         const bool has_next = S.next(ui + 1, nxt);
;         const char* nA = has_next ? (const char*)g.A + (size_t)nxt.pm * tstep : cA; const char* nB = has_next ? (const char*)g.Bt + (size_t)nxt.pn * tstep : cB;
;         for (int t = 0; t < nt; t += 2) {
;             const bool last = (t == nt - 2);
;             const char* a1 = cA + (size_t)(t + 1) * kstep;
;             const char* a2 = last ? nA : cA + (size_t)(t + 2) * kstep; const char* b2 = last ? nB : cB + (size_t)(t + 2) * kstep;
;             const char* a3 = a2 + kstep; const char* b3 = b2 + kstep;
;             if (last && has_next) S.a_ready(nxt);
;             if constexpr (SP2) {
;             PG8_LDB(B0, 0, 0); PG8_LDB(B1, 0, 1); PG8_SCHED; PG8_LDA(At, 0, 0); PG8_STAGE(PG8_SA(1, 1), a1 + hstep, voffA);
;             PG8_WAIT_V(8); PG8_WAIT_L(0); PG8_BAR; PG8_MMA(0, 0, At, B0); PG8_MMA(0, 1, At, B1); PG8_BAR; PG8_SCHED;
;             PG8_LDA(At, 0, 1); PG8_STAGE(PG8_SB(0, 0), b2, voffB); PG8_STAGE(PG8_SB(0, 1), b2 + hstep, voffB); PG8_STAGE(PG8_SA(0, 0), a2, voffA);
.LBB0_956:
	s_add_u32 s36, s46, 0x100
	s_addc_u32 s37, s47, 0
	s_mov_b32 s70, -2
	s_and_b64 s[98:99], exec, s[58:59]
	s_cbranch_scc1 .Lsp_4
	s_setprio 1
.Lsp_4:
	s_add_u32 s44, s96, 0x100
	s_addc_u32 s45, s97, 0
	s_add_i32 s8, 0, 0x10000
	s_cmp_eq_u32 s70, 40
	s_cselect_b32 s65, s67, s45
	s_cselect_b32 s64, s66, s44
	s_cselect_b32 s47, s73, s37
	s_cselect_b32 s46, s72, s36
	s_add_i32 s88, 0, 0x14000
	v_add_u32_e32 v142, s8, v185
	v_add_u32_e32 v168, s88, v185
	ds_read_b128 v[130:133], v142
	ds_read_b128 v[134:137], v142 offset:1024
	ds_read_b128 v[138:141], v142 offset:2048
	ds_read_b128 v[142:145], v142 offset:3072
	ds_read_b128 v[156:159], v168
	ds_read_b128 v[160:163], v168 offset:1024
	ds_read_b128 v[164:167], v168 offset:2048
	ds_read_b128 v[168:171], v168 offset:3072
	v_lshl_add_u64 v[208:209], s[96:97], 0, v[152:153]
	s_add_i32 m0, s15, 0xc000
	ds_read_b128 v[172:175], v191
	ds_read_b128 v[176:179], v191 offset:1024
	ds_read_b128 v[180:183], v191 offset:2048
	ds_read_b128 v[186:189], v191 offset:3072
	ds_read_b128 v[192:195], v191 offset:4096
	ds_read_b128 v[196:199], v191 offset:5120
	ds_read_b128 v[200:203], v191 offset:6144
	ds_read_b128 v[204:207], v191 offset:7168
	global_load_lds_dwordx4 v[208:209], off
	v_lshl_add_u64 v[208:209], s[96:97], 0, v[154:155]
	s_add_i32 m0, s15, 0xe000
	s_nop 0
	global_load_lds_dwordx4 v[208:209], off
	s_waitcnt vmcnt(8)
	s_waitcnt lgkmcnt(0)
	s_barrier
	s_waitcnt lgkmcnt(0)
	v_mfma_f32_16x16x32_bf16 v[124:127], v[130:133], v[172:175], 0
	v_mfma_f32_16x16x32_bf16 v[120:123], v[138:141], v[172:175], 0
	v_mfma_f32_16x16x32_bf16 v[108:111], v[130:133], v[180:183], 0
	v_mfma_f32_16x16x32_bf16 v[104:107], v[138:141], v[180:183], 0
	v_mfma_f32_16x16x32_bf16 v[92:95], v[130:133], v[192:195], 0
	v_mfma_f32_16x16x32_bf16 v[88:91], v[138:141], v[192:195], 0
	v_mfma_f32_16x16x32_bf16 v[76:79], v[130:133], v[200:203], 0
	v_mfma_f32_16x16x32_bf16 v[72:75], v[138:141], v[200:203], 0
	v_mfma_f32_16x16x32_bf16 v[124:127], v[134:137], v[176:179], v[124:127]
	v_mfma_f32_16x16x32_bf16 v[120:123], v[142:145], v[176:179], v[120:123]
	v_mfma_f32_16x16x32_bf16 v[108:111], v[134:137], v[186:189], v[108:111]
	v_mfma_f32_16x16x32_bf16 v[104:107], v[142:145], v[186:189], v[104:107]
	v_mfma_f32_16x16x32_bf16 v[92:95], v[134:137], v[196:199], v[92:95]
	v_mfma_f32_16x16x32_bf16 v[88:91], v[142:145], v[196:199], v[88:91]
	v_mfma_f32_16x16x32_bf16 v[76:79], v[134:137], v[204:207], v[76:79]
	v_mfma_f32_16x16x32_bf16 v[72:75], v[142:145], v[204:207], v[72:75]
	v_mfma_f32_16x16x32_bf16 v[116:119], v[156:159], v[172:175], 0
	v_mfma_f32_16x16x32_bf16 v[112:115], v[164:167], v[172:175], 0
	v_mfma_f32_16x16x32_bf16 v[100:103], v[156:159], v[180:183], 0
	v_mfma_f32_16x16x32_bf16 v[96:99], v[164:167], v[180:183], 0
	v_mfma_f32_16x16x32_bf16 v[84:87], v[156:159], v[192:195], 0
	v_mfma_f32_16x16x32_bf16 v[80:83], v[164:167], v[192:195], 0
	v_mfma_f32_16x16x32_bf16 v[68:71], v[156:159], v[200:203], 0
	v_mfma_f32_16x16x32_bf16 v[64:67], v[164:167], v[200:203], 0
	v_mfma_f32_16x16x32_bf16 v[116:119], v[160:163], v[176:179], v[116:119]
	v_mfma_f32_16x16x32_bf16 v[112:115], v[168:171], v[176:179], v[112:115]
	v_mfma_f32_16x16x32_bf16 v[100:103], v[160:163], v[186:189], v[100:103]
	v_mfma_f32_16x16x32_bf16 v[96:99], v[168:171], v[186:189], v[96:99]
	v_mfma_f32_16x16x32_bf16 v[84:87], v[160:163], v[196:199], v[84:87]
	v_mfma_f32_16x16x32_bf16 v[80:83], v[168:171], v[196:199], v[80:83]
	v_mfma_f32_16x16x32_bf16 v[68:71], v[160:163], v[204:207], v[68:71]
	v_mfma_f32_16x16x32_bf16 v[64:67], v[168:171], v[204:207], v[64:67]
	s_barrier
	s_add_i32 s8, s8, s14
	v_lshl_add_u64 v[208:209], s[46:47], 0, v[128:129]
	s_mov_b32 m0, s8
	ds_read_b128 v[172:175], v191 offset:16384
	ds_read_b128 v[176:179], v191 offset:17408
	ds_read_b128 v[180:183], v191 offset:18432
	ds_read_b128 v[186:189], v191 offset:19456
	ds_read_b128 v[192:195], v191 offset:20480
	ds_read_b128 v[196:199], v191 offset:21504
	ds_read_b128 v[200:203], v191 offset:22528
	ds_read_b128 v[204:207], v191 offset:23552
	global_load_lds_dwordx4 v[208:209], off
	s_add_i32 m0, s8, 0x2000
	s_add_u32 s84, s46, 0xb0000
	v_lshl_add_u64 v[210:211], s[46:47], 0, v[146:147]
	s_addc_u32 s85, s47, 0
	s_add_i32 s8, s88, s14
	global_load_lds_dwordx4 v[210:211], off
	v_lshl_add_u64 v[214:215], s[84:85], 0, v[128:129]
	s_mov_b32 m0, s8
	v_lshl_add_u64 v[222:223], s[64:65], 0, v[148:149]
	global_load_lds_dwordx4 v[214:215], off
	v_lshl_add_u64 v[214:215], s[84:85], 0, v[146:147]
	s_add_i32 m0, s8, 0x2000
	s_nop 0
	global_load_lds_dwordx4 v[214:215], off
	v_lshl_add_u64 v[214:215], s[64:65], 0, v[150:151]
	s_mov_b32 m0, s15
	s_nop 0
	global_load_lds_dwordx4 v[214:215], off
	s_mov_b32 m0, s18
	s_nop 0
	global_load_lds_dwordx4 v[222:223], off
	s_waitcnt vmcnt(8)
	s_waitcnt lgkmcnt(0)
	s_barrier
; #define PG8_STAGE(bufoff, gbase, voff) do { _Pragma("unroll") for (int _i = 0; _i < 2; ++_i) \
;         __builtin_amdgcn_global_load_lds((const unsigned*)((const char*)(gbase) + (voff)[_i]), (PG8_LAS unsigned*)(lds + (bufoff) + ldsw + _i * 8192), 16, 0, 0); } while (0)
; #define PG8_LDA(dst, b, h) do { _Pragma("unroll") for (int m = 0; m < 4; ++m) _Pragma("unroll") for (int k = 0; k < 2; ++k) dst[m][k] = *(const PG8_LAS bf16x8*)(lds + PG8_SA(b, h) + aoff + m * 2048 + k * 1024); } while (0)
; #define PG8_LDB(dst, b, h) do { _Pragma("unroll") for (int n = 0; n < 2; ++n) _Pragma("unroll") for (int k = 0; k < 2; ++k) dst[n][k] = *(const PG8_LAS bf16x8*)(lds + PG8_SB(b, h) + boff + n * 2048 + k * 1024); } while (0)
; #define PG8_MMA(ai, bj, At, Bt) do { __builtin_amdgcn_s_setprio(1); _Pragma("unroll") for (int m = 0; m < 4; ++m) _Pragma("unroll") for (int n = 0; n < 2; ++n) _Pragma("unroll") for (int k = 0; k < 2; ++k) \
;         acc[ai][bj][m][n] = __builtin_amdgcn_mfma_f32_16x16x32_bf16(Bt[n][k], At[m][k], acc[ai][bj][m][n], 0, 0, 0); __builtin_amdgcn_s_setprio(0); } while (0)
; #define PG8_WAIT_V(n) asm volatile("s_waitcnt vmcnt(" #n ")" ::: "memory")
; #define PG8_WAIT_L(n) asm volatile("s_waitcnt lgkmcnt(" #n ")" ::: "memory")
; #define PG8_BAR __builtin_amdgcn_s_barrier()
; #define PG8_SCHED __builtin_amdgcn_sched_barrier(0)
; template <class Epi, class Sched, bool ALIGN_EPI = false, bool SP2 = false>
; __device__ __forceinline__ void gemm_phase(PG8_LAS unsigned char* lds, const Gemm g, const Sched& S, const Epi& E) {
;     ...
;             PG8_WAIT_V(8); PG8_WAIT_L(0); PG8_BAR; PG8_MMA(1, 0, At, B0); PG8_MMA(1, 1, At, B1); PG8_BAR; PG8_SCHED;
;             PG8_LDB(B0, 1, 0); PG8_LDB(B1, 1, 1); PG8_SCHED; PG8_LDA(At, 1, 0); PG8_STAGE(PG8_SA(0, 1), a2 + hstep, voffA);
;             PG8_WAIT_V(8); PG8_WAIT_L(0); PG8_BAR; PG8_MMA(0, 0, At, B0); PG8_MMA(0, 1, At, B1); PG8_BAR; PG8_SCHED;
	s_waitcnt lgkmcnt(0)
	v_mfma_f32_16x16x32_bf16 v[60:63], v[130:133], v[172:175], 0
	v_mfma_f32_16x16x32_bf16 v[56:59], v[138:141], v[172:175], 0
	v_mfma_f32_16x16x32_bf16 v[44:47], v[130:133], v[180:183], 0
	v_mfma_f32_16x16x32_bf16 v[40:43], v[138:141], v[180:183], 0
	v_mfma_f32_16x16x32_bf16 v[28:31], v[130:133], v[192:195], 0
	v_mfma_f32_16x16x32_bf16 v[24:27], v[138:141], v[192:195], 0
	v_mfma_f32_16x16x32_bf16 v[12:15], v[130:133], v[200:203], 0
	v_mfma_f32_16x16x32_bf16 v[8:11], v[138:141], v[200:203], 0
	v_mfma_f32_16x16x32_bf16 v[60:63], v[134:137], v[176:179], v[60:63]
	v_mfma_f32_16x16x32_bf16 v[56:59], v[142:145], v[176:179], v[56:59]
	v_mfma_f32_16x16x32_bf16 v[44:47], v[134:137], v[186:189], v[44:47]
	v_mfma_f32_16x16x32_bf16 v[40:43], v[142:145], v[186:189], v[40:43]
	v_mfma_f32_16x16x32_bf16 v[28:31], v[134:137], v[196:199], v[28:31]
	v_mfma_f32_16x16x32_bf16 v[24:27], v[142:145], v[196:199], v[24:27]
	v_mfma_f32_16x16x32_bf16 v[12:15], v[134:137], v[204:207], v[12:15]
	v_mfma_f32_16x16x32_bf16 v[8:11], v[142:145], v[204:207], v[8:11]
	v_mfma_f32_16x16x32_bf16 v[52:55], v[156:159], v[172:175], 0
	v_mfma_f32_16x16x32_bf16 v[48:51], v[164:167], v[172:175], 0
	v_mfma_f32_16x16x32_bf16 v[36:39], v[156:159], v[180:183], 0
	v_mfma_f32_16x16x32_bf16 v[32:35], v[164:167], v[180:183], 0
	v_mfma_f32_16x16x32_bf16 v[20:23], v[156:159], v[192:195], 0
	v_mfma_f32_16x16x32_bf16 v[16:19], v[164:167], v[192:195], 0
	v_mfma_f32_16x16x32_bf16 v[4:7], v[156:159], v[200:203], 0
	v_mfma_f32_16x16x32_bf16 v[0:3], v[164:167], v[200:203], 0
	v_mfma_f32_16x16x32_bf16 v[52:55], v[160:163], v[176:179], v[52:55]
	v_mfma_f32_16x16x32_bf16 v[48:51], v[168:171], v[176:179], v[48:51]
	v_mfma_f32_16x16x32_bf16 v[36:39], v[160:163], v[186:189], v[36:39]
	v_mfma_f32_16x16x32_bf16 v[32:35], v[168:171], v[186:189], v[32:35]
	v_mfma_f32_16x16x32_bf16 v[20:23], v[160:163], v[196:199], v[20:23]
	v_mfma_f32_16x16x32_bf16 v[16:19], v[168:171], v[196:199], v[16:19]
	v_mfma_f32_16x16x32_bf16 v[4:7], v[160:163], v[204:207], v[4:7]
	v_mfma_f32_16x16x32_bf16 v[0:3], v[168:171], v[204:207], v[0:3]
	s_barrier
	s_add_i32 s8, 0, 0x18000
	s_add_i32 s84, 0, 0x1c000
	v_add_u32_e32 v142, s8, v185
	v_add_u32_e32 v168, s84, v185
	ds_read_b128 v[130:133], v142
	ds_read_b128 v[134:137], v142 offset:1024
	ds_read_b128 v[138:141], v142 offset:2048
	ds_read_b128 v[142:145], v142 offset:3072
	ds_read_b128 v[156:159], v168
	ds_read_b128 v[160:163], v168 offset:1024
	ds_read_b128 v[164:167], v168 offset:2048
	ds_read_b128 v[168:171], v168 offset:3072
	s_add_u32 s64, s64, 0xb0000
	s_addc_u32 s65, s65, 0
	s_mov_b32 m0, s19
	v_lshl_add_u64 v[228:229], s[64:65], 0, v[150:151]
	ds_read_b128 v[172:175], v191 offset:32768
	ds_read_b128 v[176:179], v191 offset:33792
	ds_read_b128 v[180:183], v191 offset:34816
	ds_read_b128 v[186:189], v191 offset:35840
	ds_read_b128 v[192:195], v191 offset:36864
	ds_read_b128 v[196:199], v191 offset:37888
	ds_read_b128 v[200:203], v191 offset:38912
	ds_read_b128 v[204:207], v191 offset:39936
	global_load_lds_dwordx4 v[228:229], off
	v_lshl_add_u64 v[228:229], s[64:65], 0, v[148:149]
	s_mov_b32 m0, s20
	s_nop 0
	global_load_lds_dwordx4 v[228:229], off
	s_waitcnt vmcnt(8)
	s_waitcnt lgkmcnt(0)
	s_barrier
	s_waitcnt lgkmcnt(0)
	v_mfma_f32_16x16x32_bf16 v[124:127], v[130:133], v[172:175], v[124:127]
	v_mfma_f32_16x16x32_bf16 v[120:123], v[138:141], v[172:175], v[120:123]
	v_mfma_f32_16x16x32_bf16 v[108:111], v[130:133], v[180:183], v[108:111]
	v_mfma_f32_16x16x32_bf16 v[104:107], v[138:141], v[180:183], v[104:107]
	v_mfma_f32_16x16x32_bf16 v[92:95], v[130:133], v[192:195], v[92:95]
	v_mfma_f32_16x16x32_bf16 v[88:91], v[138:141], v[192:195], v[88:91]
	v_mfma_f32_16x16x32_bf16 v[76:79], v[130:133], v[200:203], v[76:79]
	v_mfma_f32_16x16x32_bf16 v[72:75], v[138:141], v[200:203], v[72:75]
	v_mfma_f32_16x16x32_bf16 v[124:127], v[134:137], v[176:179], v[124:127]
	v_mfma_f32_16x16x32_bf16 v[120:123], v[142:145], v[176:179], v[120:123]
	v_mfma_f32_16x16x32_bf16 v[108:111], v[134:137], v[186:189], v[108:111]
	v_mfma_f32_16x16x32_bf16 v[104:107], v[142:145], v[186:189], v[104:107]
	v_mfma_f32_16x16x32_bf16 v[92:95], v[134:137], v[196:199], v[92:95]
	v_mfma_f32_16x16x32_bf16 v[88:91], v[142:145], v[196:199], v[88:91]
	v_mfma_f32_16x16x32_bf16 v[76:79], v[134:137], v[204:207], v[76:79]
	v_mfma_f32_16x16x32_bf16 v[72:75], v[142:145], v[204:207], v[72:75]
	v_mfma_f32_16x16x32_bf16 v[116:119], v[156:159], v[172:175], v[116:119]
	v_mfma_f32_16x16x32_bf16 v[112:115], v[164:167], v[172:175], v[112:115]
	v_mfma_f32_16x16x32_bf16 v[100:103], v[156:159], v[180:183], v[100:103]
	v_mfma_f32_16x16x32_bf16 v[96:99], v[164:167], v[180:183], v[96:99]
	v_mfma_f32_16x16x32_bf16 v[84:87], v[156:159], v[192:195], v[84:87]
	v_mfma_f32_16x16x32_bf16 v[80:83], v[164:167], v[192:195], v[80:83]
	v_mfma_f32_16x16x32_bf16 v[68:71], v[156:159], v[200:203], v[68:71]
	v_mfma_f32_16x16x32_bf16 v[64:67], v[164:167], v[200:203], v[64:67]
	v_mfma_f32_16x16x32_bf16 v[116:119], v[160:163], v[176:179], v[116:119]
	v_mfma_f32_16x16x32_bf16 v[112:115], v[168:171], v[176:179], v[112:115]
	v_mfma_f32_16x16x32_bf16 v[100:103], v[160:163], v[186:189], v[100:103]
	v_mfma_f32_16x16x32_bf16 v[96:99], v[168:171], v[186:189], v[96:99]
	v_mfma_f32_16x16x32_bf16 v[84:87], v[160:163], v[196:199], v[84:87]
	v_mfma_f32_16x16x32_bf16 v[80:83], v[168:171], v[196:199], v[80:83]
	v_mfma_f32_16x16x32_bf16 v[68:71], v[160:163], v[204:207], v[68:71]
	v_mfma_f32_16x16x32_bf16 v[64:67], v[168:171], v[204:207], v[64:67]
	s_barrier
; #define PG8_STAGE(bufoff, gbase, voff) do { _Pragma("unroll") for (int _i = 0; _i < 2; ++_i) \
;         __builtin_amdgcn_global_load_lds((const unsigned*)((const char*)(gbase) + (voff)[_i]), (PG8_LAS unsigned*)(lds + (bufoff) + ldsw + _i * 8192), 16, 0, 0); } while (0)
; #define PG8_LDA(dst, b, h) do { _Pragma("unroll") for (int m = 0; m < 4; ++m) _Pragma("unroll") for (int k = 0; k < 2; ++k) dst[m][k] = *(const PG8_LAS bf16x8*)(lds + PG8_SA(b, h) + aoff + m * 2048 + k * 1024); } while (0)
; #define PG8_MMA(ai, bj, At, Bt) do { __builtin_amdgcn_s_setprio(1); _Pragma("unroll") for (int m = 0; m < 4; ++m) _Pragma("unroll") for (int n = 0; n < 2; ++n) _Pragma("unroll") for (int k = 0; k < 2; ++k) \
;         acc[ai][bj][m][n] = __builtin_amdgcn_mfma_f32_16x16x32_bf16(Bt[n][k], At[m][k], acc[ai][bj][m][n], 0, 0, 0); __builtin_amdgcn_s_setprio(0); } while (0)
; #define PG8_WAIT_V(n) asm volatile("s_waitcnt vmcnt(" #n ")" ::: "memory")
; #define PG8_WAIT_L(n) asm volatile("s_waitcnt lgkmcnt(" #n ")" ::: "memory")
; #define PG8_BAR __builtin_amdgcn_s_barrier()
; #define PG8_SCHED __builtin_amdgcn_sched_barrier(0)
; template <class Epi, class Sched, bool ALIGN_EPI = false, bool SP2 = false>
; __device__ __forceinline__ void gemm_phase(PG8_LAS unsigned char* lds, const Gemm g, const Sched& S, const Epi& E) {
;     ...
;         for (int t = 0; t < nt; t += 2) {
;             const bool last = (t == nt - 2);
;     ...
;             PG8_LDA(At, 1, 1); PG8_STAGE(PG8_SB(1, 0), b3, voffB); PG8_STAGE(PG8_SB(1, 1), b3 + hstep, voffB); PG8_STAGE(PG8_SA(1, 0), a3, voffA);
;             PG8_WAIT_V(8); PG8_WAIT_L(0); PG8_BAR; PG8_MMA(1, 0, At, B0); PG8_MMA(1, 1, At, B1); PG8_BAR; PG8_SCHED;
	s_add_i32 s8, s8, s14
	v_lshl_add_u64 v[208:209], v[208:209], 0, s[90:91]
	s_mov_b32 m0, s8
	ds_read_b128 v[172:175], v191 offset:49152
	ds_read_b128 v[176:179], v191 offset:50176
	ds_read_b128 v[180:183], v191 offset:51200
	ds_read_b128 v[186:189], v191 offset:52224
	ds_read_b128 v[192:195], v191 offset:53248
	ds_read_b128 v[196:199], v191 offset:54272
	ds_read_b128 v[200:203], v191 offset:55296
	ds_read_b128 v[204:207], v191 offset:56320
	global_load_lds_dwordx4 v[208:209], off
	s_add_i32 m0, s8, 0x2000
	s_add_u32 s46, s46, 0xb0080
	v_lshl_add_u64 v[208:209], v[210:211], 0, s[90:91]
	s_addc_u32 s47, s47, 0
	s_add_i32 s8, s84, s14
	global_load_lds_dwordx4 v[208:209], off
	v_lshl_add_u64 v[208:209], s[46:47], 0, v[128:129]
	s_mov_b32 m0, s8
	s_nop 0
	global_load_lds_dwordx4 v[208:209], off
	v_lshl_add_u64 v[208:209], s[46:47], 0, v[146:147]
	s_add_i32 m0, s8, 0x2000
	s_nop 0
	global_load_lds_dwordx4 v[208:209], off
	v_lshl_add_u64 v[208:209], v[214:215], 0, s[90:91]
	s_mov_b32 m0, s27
	s_nop 0
	global_load_lds_dwordx4 v[208:209], off
	v_lshl_add_u64 v[208:209], v[222:223], 0, s[90:91]
	s_mov_b32 m0, s28
	s_nop 0
	global_load_lds_dwordx4 v[208:209], off
	s_waitcnt vmcnt(8)
	s_waitcnt lgkmcnt(0)
	s_barrier
	s_waitcnt lgkmcnt(0)
	v_mfma_f32_16x16x32_bf16 v[60:63], v[130:133], v[172:175], v[60:63]
	v_mfma_f32_16x16x32_bf16 v[56:59], v[138:141], v[172:175], v[56:59]
	v_mfma_f32_16x16x32_bf16 v[44:47], v[130:133], v[180:183], v[44:47]
	v_mfma_f32_16x16x32_bf16 v[40:43], v[138:141], v[180:183], v[40:43]
	v_mfma_f32_16x16x32_bf16 v[28:31], v[130:133], v[192:195], v[28:31]
	v_mfma_f32_16x16x32_bf16 v[24:27], v[138:141], v[192:195], v[24:27]
	v_mfma_f32_16x16x32_bf16 v[12:15], v[130:133], v[200:203], v[12:15]
	v_mfma_f32_16x16x32_bf16 v[8:11], v[138:141], v[200:203], v[8:11]
	v_mfma_f32_16x16x32_bf16 v[60:63], v[134:137], v[176:179], v[60:63]
	v_mfma_f32_16x16x32_bf16 v[56:59], v[142:145], v[176:179], v[56:59]
	v_mfma_f32_16x16x32_bf16 v[44:47], v[134:137], v[186:189], v[44:47]
	v_mfma_f32_16x16x32_bf16 v[40:43], v[142:145], v[186:189], v[40:43]
	v_mfma_f32_16x16x32_bf16 v[28:31], v[134:137], v[196:199], v[28:31]
	v_mfma_f32_16x16x32_bf16 v[24:27], v[142:145], v[196:199], v[24:27]
	v_mfma_f32_16x16x32_bf16 v[12:15], v[134:137], v[204:207], v[12:15]
	v_mfma_f32_16x16x32_bf16 v[8:11], v[142:145], v[204:207], v[8:11]
	v_mfma_f32_16x16x32_bf16 v[52:55], v[156:159], v[172:175], v[52:55]
	v_mfma_f32_16x16x32_bf16 v[48:51], v[164:167], v[172:175], v[48:51]
	v_mfma_f32_16x16x32_bf16 v[36:39], v[156:159], v[180:183], v[36:39]
	v_mfma_f32_16x16x32_bf16 v[32:35], v[164:167], v[180:183], v[32:35]
	v_mfma_f32_16x16x32_bf16 v[20:23], v[156:159], v[192:195], v[20:23]
	v_mfma_f32_16x16x32_bf16 v[16:19], v[164:167], v[192:195], v[16:19]
	v_mfma_f32_16x16x32_bf16 v[4:7], v[156:159], v[200:203], v[4:7]
	v_mfma_f32_16x16x32_bf16 v[0:3], v[164:167], v[200:203], v[0:3]
	v_mfma_f32_16x16x32_bf16 v[52:55], v[160:163], v[176:179], v[52:55]
	v_mfma_f32_16x16x32_bf16 v[48:51], v[168:171], v[176:179], v[48:51]
	v_mfma_f32_16x16x32_bf16 v[36:39], v[160:163], v[186:189], v[36:39]
	v_mfma_f32_16x16x32_bf16 v[32:35], v[168:171], v[186:189], v[32:35]
	v_mfma_f32_16x16x32_bf16 v[20:23], v[160:163], v[196:199], v[20:23]
	v_mfma_f32_16x16x32_bf16 v[16:19], v[168:171], v[196:199], v[16:19]
	v_mfma_f32_16x16x32_bf16 v[4:7], v[160:163], v[204:207], v[4:7]
	v_mfma_f32_16x16x32_bf16 v[0:3], v[168:171], v[204:207], v[0:3]
	s_barrier
	s_add_i32 s70, s70, 2
	s_add_u32 s36, s36, 0x100
	s_addc_u32 s37, s37, 0
	s_cmp_gt_u32 s70, 41
	s_mov_b64 s[96:97], s[44:45]
	s_cbranch_scc1 .Lpeel_x4

; #define PG8_BAR __builtin_amdgcn_s_barrier()
; template <class Epi, class Sched, bool ALIGN_EPI = false, bool SP2 = false>
; __device__ __forceinline__ void gemm_phase(PG8_LAS unsigned char* lds, const Gemm g, const Sched& S, const Epi& E) {
;     ...
;         if constexpr (ALIGN_EPI) { if (wr == 0) PG8_BAR; }
.Lpeel_x4:
	s_setprio 0
	s_and_b64 vcc, exec, s[58:59]
	s_cbranch_vccz .LBB0_960
	s_barrier

; #define PG8_STAGE(bufoff, gbase, voff) do { _Pragma("unroll") for (int _i = 0; _i < 2; ++_i) \
;         __builtin_amdgcn_global_load_lds((const unsigned*)((const char*)(gbase) + (voff)[_i]), (PG8_LAS unsigned*)(lds + (bufoff) + ldsw + _i * 8192), 16, 0, 0); } while (0)
; #define PG8_LDA(dst, b, h) do { _Pragma("unroll") for (int m = 0; m < 4; ++m) _Pragma("unroll") for (int k = 0; k < 2; ++k) dst[m][k] = *(const PG8_LAS bf16x8*)(lds + PG8_SA(b, h) + aoff + m * 2048 + k * 1024); } while (0)
; #define PG8_LDB(dst, b, h) do { _Pragma("unroll") for (int n = 0; n < 2; ++n) _Pragma("unroll") for (int k = 0; k < 2; ++k) dst[n][k] = *(const PG8_LAS bf16x8*)(lds + PG8_SB(b, h) + boff + n * 2048 + k * 1024); } while (0)
; #define PG8_MMA(ai, bj, At, Bt) do { __builtin_amdgcn_s_setprio(1); _Pragma("unroll") for (int m = 0; m < 4; ++m) _Pragma("unroll") for (int n = 0; n < 2; ++n) _Pragma("unroll") for (int k = 0; k < 2; ++k) \
;         acc[ai][bj][m][n] = __builtin_amdgcn_mfma_f32_16x16x32_bf16(Bt[n][k], At[m][k], acc[ai][bj][m][n], 0, 0, 0); __builtin_amdgcn_s_setprio(0); } while (0)
; #define PG8_BAR __builtin_amdgcn_s_barrier()
; template <class Epi, class Sched, bool ALIGN_EPI = false, bool SP2 = false>
; __device__ __forceinline__ void gemm_phase(PG8_LAS unsigned char* lds, const Gemm g, const Sched& S, const Epi& E) {
;     ...
;         const bool has_next = S.next(ui + 1, nxt);
;         const char* nA = has_next ? (const char*)g.A + (size_t)nxt.pm * tstep : cA; const char* nB = has_next ? (const char*)g.Bt + (size_t)nxt.pn * tstep : cB;
;         for (int t = 0; t < nt; t += 2) {
;             const bool last = (t == nt - 2);
;             const char* a1 = cA + (size_t)(t + 1) * kstep;
;             const char* a2 = last ? nA : cA + (size_t)(t + 2) * kstep; const char* b2 = last ? nB : cB + (size_t)(t + 2) * kstep;
;             const char* a3 = a2 + kstep; const char* b3 = b2 + kstep;
;             if (last && has_next) S.a_ready(nxt);
;             if constexpr (SP2) {
;             PG8_LDB(B0, 0, 0); PG8_LDB(B1, 0, 1); PG8_SCHED; PG8_LDA(At, 0, 0); PG8_STAGE(PG8_SA(1, 1), a1 + hstep, voffA);
;             PG8_WAIT_V(8); PG8_WAIT_L(0); PG8_BAR; PG8_MMA(0, 0, At, B0); PG8_MMA(0, 1, At, B1); PG8_BAR; PG8_SCHED;
;             PG8_LDA(At, 0, 1); PG8_STAGE(PG8_SB(0, 0), b2, voffB); PG8_STAGE(PG8_SB(0, 1), b2 + hstep, voffB); PG8_STAGE(PG8_SA(0, 0), a2, voffA);
.LBB0_994:
	s_add_u32 s36, s46, 0x100
	s_addc_u32 s37, s47, 0
	s_mov_b32 s84, -2
	s_and_b64 s[98:99], exec, s[62:63]
	s_cbranch_scc1 .Lsp_5
	s_setprio 1
.Lsp_5:
	s_add_u32 s42, s96, 0x100
	s_addc_u32 s43, s97, 0
	s_add_i32 s8, 0, 0x10000
	s_cmp_eq_u32 s84, 40
	s_cselect_b32 s65, s67, s43
	s_cselect_b32 s64, s66, s42
	s_cselect_b32 s47, s73, s37
	s_cselect_b32 s46, s72, s36
	s_add_i32 s85, 0, 0x14000
	v_add_u32_e32 v142, s8, v201
	v_add_u32_e32 v168, s85, v201
	ds_read_b128 v[130:133], v142
	ds_read_b128 v[134:137], v142 offset:1024
	ds_read_b128 v[138:141], v142 offset:2048
	ds_read_b128 v[142:145], v142 offset:3072
	ds_read_b128 v[156:159], v168
	ds_read_b128 v[160:163], v168 offset:1024
	ds_read_b128 v[164:167], v168 offset:2048
	ds_read_b128 v[168:171], v168 offset:3072
	v_lshl_add_u64 v[208:209], s[96:97], 0, v[152:153]
	s_add_i32 m0, s15, 0xc000
	ds_read_b128 v[172:175], v203
	ds_read_b128 v[176:179], v203 offset:1024
	ds_read_b128 v[180:183], v203 offset:2048
	ds_read_b128 v[184:187], v203 offset:3072
	ds_read_b128 v[188:191], v203 offset:4096
	ds_read_b128 v[192:195], v203 offset:5120
	ds_read_b128 v[196:199], v203 offset:6144
	ds_read_b128 v[204:207], v203 offset:7168
	global_load_lds_dwordx4 v[208:209], off
	v_lshl_add_u64 v[208:209], s[96:97], 0, v[154:155]
	s_add_i32 m0, s15, 0xe000
	s_nop 0
	global_load_lds_dwordx4 v[208:209], off
	s_waitcnt vmcnt(8)
	s_waitcnt lgkmcnt(0)
	s_barrier
	s_waitcnt lgkmcnt(0)
	v_mfma_f32_16x16x32_bf16 v[124:127], v[130:133], v[172:175], 0
	v_mfma_f32_16x16x32_bf16 v[120:123], v[138:141], v[172:175], 0
	v_mfma_f32_16x16x32_bf16 v[108:111], v[130:133], v[180:183], 0
	v_mfma_f32_16x16x32_bf16 v[104:107], v[138:141], v[180:183], 0
	v_mfma_f32_16x16x32_bf16 v[92:95], v[130:133], v[188:191], 0
	v_mfma_f32_16x16x32_bf16 v[88:91], v[138:141], v[188:191], 0
	v_mfma_f32_16x16x32_bf16 v[76:79], v[130:133], v[196:199], 0
	v_mfma_f32_16x16x32_bf16 v[72:75], v[138:141], v[196:199], 0
	v_mfma_f32_16x16x32_bf16 v[124:127], v[134:137], v[176:179], v[124:127]
	v_mfma_f32_16x16x32_bf16 v[120:123], v[142:145], v[176:179], v[120:123]
	v_mfma_f32_16x16x32_bf16 v[108:111], v[134:137], v[184:187], v[108:111]
	v_mfma_f32_16x16x32_bf16 v[104:107], v[142:145], v[184:187], v[104:107]
	v_mfma_f32_16x16x32_bf16 v[92:95], v[134:137], v[192:195], v[92:95]
	v_mfma_f32_16x16x32_bf16 v[88:91], v[142:145], v[192:195], v[88:91]
	v_mfma_f32_16x16x32_bf16 v[76:79], v[134:137], v[204:207], v[76:79]
	v_mfma_f32_16x16x32_bf16 v[72:75], v[142:145], v[204:207], v[72:75]
	v_mfma_f32_16x16x32_bf16 v[116:119], v[156:159], v[172:175], 0
	v_mfma_f32_16x16x32_bf16 v[112:115], v[164:167], v[172:175], 0
	v_mfma_f32_16x16x32_bf16 v[100:103], v[156:159], v[180:183], 0
	v_mfma_f32_16x16x32_bf16 v[96:99], v[164:167], v[180:183], 0
	v_mfma_f32_16x16x32_bf16 v[84:87], v[156:159], v[188:191], 0
	v_mfma_f32_16x16x32_bf16 v[80:83], v[164:167], v[188:191], 0
	v_mfma_f32_16x16x32_bf16 v[68:71], v[156:159], v[196:199], 0
	v_mfma_f32_16x16x32_bf16 v[64:67], v[164:167], v[196:199], 0
	v_mfma_f32_16x16x32_bf16 v[116:119], v[160:163], v[176:179], v[116:119]
	v_mfma_f32_16x16x32_bf16 v[112:115], v[168:171], v[176:179], v[112:115]
	v_mfma_f32_16x16x32_bf16 v[100:103], v[160:163], v[184:187], v[100:103]
	v_mfma_f32_16x16x32_bf16 v[96:99], v[168:171], v[184:187], v[96:99]
	v_mfma_f32_16x16x32_bf16 v[84:87], v[160:163], v[192:195], v[84:87]
	v_mfma_f32_16x16x32_bf16 v[80:83], v[168:171], v[192:195], v[80:83]
	v_mfma_f32_16x16x32_bf16 v[68:71], v[160:163], v[204:207], v[68:71]
	v_mfma_f32_16x16x32_bf16 v[64:67], v[168:171], v[204:207], v[64:67]
	s_barrier
	s_add_i32 s8, s8, s14
	v_lshl_add_u64 v[208:209], s[46:47], 0, v[128:129]
	s_mov_b32 m0, s8
	ds_read_b128 v[172:175], v203 offset:16384
	ds_read_b128 v[176:179], v203 offset:17408
	ds_read_b128 v[180:183], v203 offset:18432
	ds_read_b128 v[184:187], v203 offset:19456
	ds_read_b128 v[188:191], v203 offset:20480
	ds_read_b128 v[192:195], v203 offset:21504
	ds_read_b128 v[196:199], v203 offset:22528
	ds_read_b128 v[204:207], v203 offset:23552
	global_load_lds_dwordx4 v[208:209], off
	s_add_i32 m0, s8, 0x2000
	s_add_u32 s96, s46, 0xb0000
	v_lshl_add_u64 v[210:211], s[46:47], 0, v[146:147]
	s_addc_u32 s97, s47, 0
	s_add_i32 s8, s85, s14
	global_load_lds_dwordx4 v[210:211], off
	v_lshl_add_u64 v[214:215], s[96:97], 0, v[128:129]
	s_mov_b32 m0, s8
	v_lshl_add_u64 v[222:223], s[64:65], 0, v[148:149]
	global_load_lds_dwordx4 v[214:215], off
	v_lshl_add_u64 v[214:215], s[96:97], 0, v[146:147]
	s_add_i32 m0, s8, 0x2000
	s_nop 0
	global_load_lds_dwordx4 v[214:215], off
	v_lshl_add_u64 v[214:215], s[64:65], 0, v[150:151]
	s_mov_b32 m0, s15
	s_nop 0
	global_load_lds_dwordx4 v[214:215], off
	s_mov_b32 m0, s18
	s_nop 0
	global_load_lds_dwordx4 v[222:223], off
	s_waitcnt vmcnt(8)
	s_waitcnt lgkmcnt(0)
	s_barrier
; #define PG8_STAGE(bufoff, gbase, voff) do { _Pragma("unroll") for (int _i = 0; _i < 2; ++_i) \
;         __builtin_amdgcn_global_load_lds((const unsigned*)((const char*)(gbase) + (voff)[_i]), (PG8_LAS unsigned*)(lds + (bufoff) + ldsw + _i * 8192), 16, 0, 0); } while (0)
; #define PG8_LDA(dst, b, h) do { _Pragma("unroll") for (int m = 0; m < 4; ++m) _Pragma("unroll") for (int k = 0; k < 2; ++k) dst[m][k] = *(const PG8_LAS bf16x8*)(lds + PG8_SA(b, h) + aoff + m * 2048 + k * 1024); } while (0)
; #define PG8_LDB(dst, b, h) do { _Pragma("unroll") for (int n = 0; n < 2; ++n) _Pragma("unroll") for (int k = 0; k < 2; ++k) dst[n][k] = *(const PG8_LAS bf16x8*)(lds + PG8_SB(b, h) + boff + n * 2048 + k * 1024); } while (0)
; #define PG8_MMA(ai, bj, At, Bt) do { __builtin_amdgcn_s_setprio(1); _Pragma("unroll") for (int m = 0; m < 4; ++m) _Pragma("unroll") for (int n = 0; n < 2; ++n) _Pragma("unroll") for (int k = 0; k < 2; ++k) \
;         acc[ai][bj][m][n] = __builtin_amdgcn_mfma_f32_16x16x32_bf16(Bt[n][k], At[m][k], acc[ai][bj][m][n], 0, 0, 0); __builtin_amdgcn_s_setprio(0); } while (0)
; #define PG8_WAIT_V(n) asm volatile("s_waitcnt vmcnt(" #n ")" ::: "memory")
; #define PG8_WAIT_L(n) asm volatile("s_waitcnt lgkmcnt(" #n ")" ::: "memory")
; #define PG8_BAR __builtin_amdgcn_s_barrier()
; #define PG8_SCHED __builtin_amdgcn_sched_barrier(0)
; template <class Epi, class Sched, bool ALIGN_EPI = false, bool SP2 = false>
; __device__ __forceinline__ void gemm_phase(PG8_LAS unsigned char* lds, const Gemm g, const Sched& S, const Epi& E) {
;     ...
;             PG8_WAIT_V(8); PG8_WAIT_L(0); PG8_BAR; PG8_MMA(1, 0, At, B0); PG8_MMA(1, 1, At, B1); PG8_BAR; PG8_SCHED;
;             PG8_LDB(B0, 1, 0); PG8_LDB(B1, 1, 1); PG8_SCHED; PG8_LDA(At, 1, 0); PG8_STAGE(PG8_SA(0, 1), a2 + hstep, voffA);
;             PG8_WAIT_V(8); PG8_WAIT_L(0); PG8_BAR; PG8_MMA(0, 0, At, B0); PG8_MMA(0, 1, At, B1); PG8_BAR; PG8_SCHED;
	s_waitcnt lgkmcnt(0)
	v_mfma_f32_16x16x32_bf16 v[60:63], v[130:133], v[172:175], 0
	v_mfma_f32_16x16x32_bf16 v[56:59], v[138:141], v[172:175], 0
	v_mfma_f32_16x16x32_bf16 v[44:47], v[130:133], v[180:183], 0
	v_mfma_f32_16x16x32_bf16 v[40:43], v[138:141], v[180:183], 0
	v_mfma_f32_16x16x32_bf16 v[28:31], v[130:133], v[188:191], 0
	v_mfma_f32_16x16x32_bf16 v[24:27], v[138:141], v[188:191], 0
	v_mfma_f32_16x16x32_bf16 v[12:15], v[130:133], v[196:199], 0
	v_mfma_f32_16x16x32_bf16 v[8:11], v[138:141], v[196:199], 0
	v_mfma_f32_16x16x32_bf16 v[60:63], v[134:137], v[176:179], v[60:63]
	v_mfma_f32_16x16x32_bf16 v[56:59], v[142:145], v[176:179], v[56:59]
	v_mfma_f32_16x16x32_bf16 v[44:47], v[134:137], v[184:187], v[44:47]
	v_mfma_f32_16x16x32_bf16 v[40:43], v[142:145], v[184:187], v[40:43]
	v_mfma_f32_16x16x32_bf16 v[28:31], v[134:137], v[192:195], v[28:31]
	v_mfma_f32_16x16x32_bf16 v[24:27], v[142:145], v[192:195], v[24:27]
	v_mfma_f32_16x16x32_bf16 v[12:15], v[134:137], v[204:207], v[12:15]
	v_mfma_f32_16x16x32_bf16 v[8:11], v[142:145], v[204:207], v[8:11]
	v_mfma_f32_16x16x32_bf16 v[52:55], v[156:159], v[172:175], 0
	v_mfma_f32_16x16x32_bf16 v[48:51], v[164:167], v[172:175], 0
	v_mfma_f32_16x16x32_bf16 v[36:39], v[156:159], v[180:183], 0
	v_mfma_f32_16x16x32_bf16 v[32:35], v[164:167], v[180:183], 0
	v_mfma_f32_16x16x32_bf16 v[20:23], v[156:159], v[188:191], 0
	v_mfma_f32_16x16x32_bf16 v[16:19], v[164:167], v[188:191], 0
	v_mfma_f32_16x16x32_bf16 v[4:7], v[156:159], v[196:199], 0
	v_mfma_f32_16x16x32_bf16 v[0:3], v[164:167], v[196:199], 0
	v_mfma_f32_16x16x32_bf16 v[52:55], v[160:163], v[176:179], v[52:55]
	v_mfma_f32_16x16x32_bf16 v[48:51], v[168:171], v[176:179], v[48:51]
	v_mfma_f32_16x16x32_bf16 v[36:39], v[160:163], v[184:187], v[36:39]
	v_mfma_f32_16x16x32_bf16 v[32:35], v[168:171], v[184:187], v[32:35]
	v_mfma_f32_16x16x32_bf16 v[20:23], v[160:163], v[192:195], v[20:23]
	v_mfma_f32_16x16x32_bf16 v[16:19], v[168:171], v[192:195], v[16:19]
	v_mfma_f32_16x16x32_bf16 v[4:7], v[160:163], v[204:207], v[4:7]
	v_mfma_f32_16x16x32_bf16 v[0:3], v[168:171], v[204:207], v[0:3]
	s_barrier
	s_add_i32 s8, 0, 0x18000
	s_add_i32 s85, 0, 0x1c000
	v_add_u32_e32 v142, s8, v201
	v_add_u32_e32 v168, s85, v201
	ds_read_b128 v[130:133], v142
	ds_read_b128 v[134:137], v142 offset:1024
	ds_read_b128 v[138:141], v142 offset:2048
	ds_read_b128 v[142:145], v142 offset:3072
	ds_read_b128 v[156:159], v168
	ds_read_b128 v[160:163], v168 offset:1024
	ds_read_b128 v[164:167], v168 offset:2048
	ds_read_b128 v[168:171], v168 offset:3072
	s_add_u32 s64, s64, 0xb0000
	s_addc_u32 s65, s65, 0
	s_mov_b32 m0, s19
	v_lshl_add_u64 v[228:229], s[64:65], 0, v[150:151]
	ds_read_b128 v[172:175], v203 offset:32768
	ds_read_b128 v[176:179], v203 offset:33792
	ds_read_b128 v[180:183], v203 offset:34816
	ds_read_b128 v[184:187], v203 offset:35840
	ds_read_b128 v[188:191], v203 offset:36864
	ds_read_b128 v[192:195], v203 offset:37888
	ds_read_b128 v[196:199], v203 offset:38912
	ds_read_b128 v[204:207], v203 offset:39936
	global_load_lds_dwordx4 v[228:229], off
	v_lshl_add_u64 v[228:229], s[64:65], 0, v[148:149]
	s_mov_b32 m0, s20
	s_nop 0
	global_load_lds_dwordx4 v[228:229], off
	s_waitcnt vmcnt(8)
	s_waitcnt lgkmcnt(0)
	s_barrier
	s_waitcnt lgkmcnt(0)
	v_mfma_f32_16x16x32_bf16 v[124:127], v[130:133], v[172:175], v[124:127]
	v_mfma_f32_16x16x32_bf16 v[120:123], v[138:141], v[172:175], v[120:123]
	v_mfma_f32_16x16x32_bf16 v[108:111], v[130:133], v[180:183], v[108:111]
	v_mfma_f32_16x16x32_bf16 v[104:107], v[138:141], v[180:183], v[104:107]
	v_mfma_f32_16x16x32_bf16 v[92:95], v[130:133], v[188:191], v[92:95]
	v_mfma_f32_16x16x32_bf16 v[88:91], v[138:141], v[188:191], v[88:91]
	v_mfma_f32_16x16x32_bf16 v[76:79], v[130:133], v[196:199], v[76:79]
	v_mfma_f32_16x16x32_bf16 v[72:75], v[138:141], v[196:199], v[72:75]
	v_mfma_f32_16x16x32_bf16 v[124:127], v[134:137], v[176:179], v[124:127]
	v_mfma_f32_16x16x32_bf16 v[120:123], v[142:145], v[176:179], v[120:123]
	v_mfma_f32_16x16x32_bf16 v[108:111], v[134:137], v[184:187], v[108:111]
	v_mfma_f32_16x16x32_bf16 v[104:107], v[142:145], v[184:187], v[104:107]
	v_mfma_f32_16x16x32_bf16 v[92:95], v[134:137], v[192:195], v[92:95]
	v_mfma_f32_16x16x32_bf16 v[88:91], v[142:145], v[192:195], v[88:91]
	v_mfma_f32_16x16x32_bf16 v[76:79], v[134:137], v[204:207], v[76:79]
	v_mfma_f32_16x16x32_bf16 v[72:75], v[142:145], v[204:207], v[72:75]
	v_mfma_f32_16x16x32_bf16 v[116:119], v[156:159], v[172:175], v[116:119]
	v_mfma_f32_16x16x32_bf16 v[112:115], v[164:167], v[172:175], v[112:115]
	v_mfma_f32_16x16x32_bf16 v[100:103], v[156:159], v[180:183], v[100:103]
	v_mfma_f32_16x16x32_bf16 v[96:99], v[164:167], v[180:183], v[96:99]
	v_mfma_f32_16x16x32_bf16 v[84:87], v[156:159], v[188:191], v[84:87]
	v_mfma_f32_16x16x32_bf16 v[80:83], v[164:167], v[188:191], v[80:83]
	v_mfma_f32_16x16x32_bf16 v[68:71], v[156:159], v[196:199], v[68:71]
	v_mfma_f32_16x16x32_bf16 v[64:67], v[164:167], v[196:199], v[64:67]
	v_mfma_f32_16x16x32_bf16 v[116:119], v[160:163], v[176:179], v[116:119]
	v_mfma_f32_16x16x32_bf16 v[112:115], v[168:171], v[176:179], v[112:115]
	v_mfma_f32_16x16x32_bf16 v[100:103], v[160:163], v[184:187], v[100:103]
	v_mfma_f32_16x16x32_bf16 v[96:99], v[168:171], v[184:187], v[96:99]
	v_mfma_f32_16x16x32_bf16 v[84:87], v[160:163], v[192:195], v[84:87]
	v_mfma_f32_16x16x32_bf16 v[80:83], v[168:171], v[192:195], v[80:83]
	v_mfma_f32_16x16x32_bf16 v[68:71], v[160:163], v[204:207], v[68:71]
	v_mfma_f32_16x16x32_bf16 v[64:67], v[168:171], v[204:207], v[64:67]
	s_barrier
; #define PG8_STAGE(bufoff, gbase, voff) do { _Pragma("unroll") for (int _i = 0; _i < 2; ++_i) \
;         __builtin_amdgcn_global_load_lds((const unsigned*)((const char*)(gbase) + (voff)[_i]), (PG8_LAS unsigned*)(lds + (bufoff) + ldsw + _i * 8192), 16, 0, 0); } while (0)
; #define PG8_LDA(dst, b, h) do { _Pragma("unroll") for (int m = 0; m < 4; ++m) _Pragma("unroll") for (int k = 0; k < 2; ++k) dst[m][k] = *(const PG8_LAS bf16x8*)(lds + PG8_SA(b, h) + aoff + m * 2048 + k * 1024); } while (0)
; #define PG8_MMA(ai, bj, At, Bt) do { __builtin_amdgcn_s_setprio(1); _Pragma("unroll") for (int m = 0; m < 4; ++m) _Pragma("unroll") for (int n = 0; n < 2; ++n) _Pragma("unroll") for (int k = 0; k < 2; ++k) \
;         acc[ai][bj][m][n] = __builtin_amdgcn_mfma_f32_16x16x32_bf16(Bt[n][k], At[m][k], acc[ai][bj][m][n], 0, 0, 0); __builtin_amdgcn_s_setprio(0); } while (0)
; #define PG8_WAIT_V(n) asm volatile("s_waitcnt vmcnt(" #n ")" ::: "memory")
; #define PG8_WAIT_L(n) asm volatile("s_waitcnt lgkmcnt(" #n ")" ::: "memory")
; #define PG8_BAR __builtin_amdgcn_s_barrier()
; #define PG8_SCHED __builtin_amdgcn_sched_barrier(0)
; template <class Epi, class Sched, bool ALIGN_EPI = false, bool SP2 = false>
; __device__ __forceinline__ void gemm_phase(PG8_LAS unsigned char* lds, const Gemm g, const Sched& S, const Epi& E) {
;     ...
;         for (int t = 0; t < nt; t += 2) {
;             const bool last = (t == nt - 2);
;     ...
;             PG8_LDA(At, 1, 1); PG8_STAGE(PG8_SB(1, 0), b3, voffB); PG8_STAGE(PG8_SB(1, 1), b3 + hstep, voffB); PG8_STAGE(PG8_SA(1, 0), a3, voffA);
;             PG8_WAIT_V(8); PG8_WAIT_L(0); PG8_BAR; PG8_MMA(1, 0, At, B0); PG8_MMA(1, 1, At, B1); PG8_BAR; PG8_SCHED;
	s_add_i32 s8, s8, s14
	v_lshl_add_u64 v[208:209], v[208:209], 0, s[90:91]
	s_mov_b32 m0, s8
	ds_read_b128 v[172:175], v203 offset:49152
	ds_read_b128 v[176:179], v203 offset:50176
	ds_read_b128 v[180:183], v203 offset:51200
	ds_read_b128 v[184:187], v203 offset:52224
	ds_read_b128 v[188:191], v203 offset:53248
	ds_read_b128 v[192:195], v203 offset:54272
	ds_read_b128 v[196:199], v203 offset:55296
	ds_read_b128 v[204:207], v203 offset:56320
	global_load_lds_dwordx4 v[208:209], off
	s_add_i32 m0, s8, 0x2000
	s_add_u32 s46, s46, 0xb0080
	v_lshl_add_u64 v[208:209], v[210:211], 0, s[90:91]
	s_addc_u32 s47, s47, 0
	s_add_i32 s8, s85, s14
	global_load_lds_dwordx4 v[208:209], off
	v_lshl_add_u64 v[208:209], s[46:47], 0, v[128:129]
	s_mov_b32 m0, s8
	s_nop 0
	global_load_lds_dwordx4 v[208:209], off
	v_lshl_add_u64 v[208:209], s[46:47], 0, v[146:147]
	s_add_i32 m0, s8, 0x2000
	s_nop 0
	global_load_lds_dwordx4 v[208:209], off
	v_lshl_add_u64 v[208:209], v[214:215], 0, s[90:91]
	s_mov_b32 m0, s29
	s_nop 0
	global_load_lds_dwordx4 v[208:209], off
	v_lshl_add_u64 v[208:209], v[222:223], 0, s[90:91]
	s_mov_b32 m0, s30
	s_nop 0
	global_load_lds_dwordx4 v[208:209], off
	s_waitcnt vmcnt(8)
	s_waitcnt lgkmcnt(0)
	s_barrier
	s_waitcnt lgkmcnt(0)
	v_mfma_f32_16x16x32_bf16 v[60:63], v[130:133], v[172:175], v[60:63]
	v_mfma_f32_16x16x32_bf16 v[56:59], v[138:141], v[172:175], v[56:59]
	v_mfma_f32_16x16x32_bf16 v[44:47], v[130:133], v[180:183], v[44:47]
	v_mfma_f32_16x16x32_bf16 v[40:43], v[138:141], v[180:183], v[40:43]
	v_mfma_f32_16x16x32_bf16 v[28:31], v[130:133], v[188:191], v[28:31]
	v_mfma_f32_16x16x32_bf16 v[24:27], v[138:141], v[188:191], v[24:27]
	v_mfma_f32_16x16x32_bf16 v[12:15], v[130:133], v[196:199], v[12:15]
	v_mfma_f32_16x16x32_bf16 v[8:11], v[138:141], v[196:199], v[8:11]
	v_mfma_f32_16x16x32_bf16 v[60:63], v[134:137], v[176:179], v[60:63]
	v_mfma_f32_16x16x32_bf16 v[56:59], v[142:145], v[176:179], v[56:59]
	v_mfma_f32_16x16x32_bf16 v[44:47], v[134:137], v[184:187], v[44:47]
	v_mfma_f32_16x16x32_bf16 v[40:43], v[142:145], v[184:187], v[40:43]
	v_mfma_f32_16x16x32_bf16 v[28:31], v[134:137], v[192:195], v[28:31]
	v_mfma_f32_16x16x32_bf16 v[24:27], v[142:145], v[192:195], v[24:27]
	v_mfma_f32_16x16x32_bf16 v[12:15], v[134:137], v[204:207], v[12:15]
	v_mfma_f32_16x16x32_bf16 v[8:11], v[142:145], v[204:207], v[8:11]
	v_mfma_f32_16x16x32_bf16 v[52:55], v[156:159], v[172:175], v[52:55]
	v_mfma_f32_16x16x32_bf16 v[48:51], v[164:167], v[172:175], v[48:51]
	v_mfma_f32_16x16x32_bf16 v[36:39], v[156:159], v[180:183], v[36:39]
	v_mfma_f32_16x16x32_bf16 v[32:35], v[164:167], v[180:183], v[32:35]
	v_mfma_f32_16x16x32_bf16 v[20:23], v[156:159], v[188:191], v[20:23]
	v_mfma_f32_16x16x32_bf16 v[16:19], v[164:167], v[188:191], v[16:19]
	v_mfma_f32_16x16x32_bf16 v[4:7], v[156:159], v[196:199], v[4:7]
	v_mfma_f32_16x16x32_bf16 v[0:3], v[164:167], v[196:199], v[0:3]
	v_mfma_f32_16x16x32_bf16 v[52:55], v[160:163], v[176:179], v[52:55]
	v_mfma_f32_16x16x32_bf16 v[48:51], v[168:171], v[176:179], v[48:51]
	v_mfma_f32_16x16x32_bf16 v[36:39], v[160:163], v[184:187], v[36:39]
	v_mfma_f32_16x16x32_bf16 v[32:35], v[168:171], v[184:187], v[32:35]
	v_mfma_f32_16x16x32_bf16 v[20:23], v[160:163], v[192:195], v[20:23]
	v_mfma_f32_16x16x32_bf16 v[16:19], v[168:171], v[192:195], v[16:19]
	v_mfma_f32_16x16x32_bf16 v[4:7], v[160:163], v[204:207], v[4:7]
	v_mfma_f32_16x16x32_bf16 v[0:3], v[168:171], v[204:207], v[0:3]
	s_barrier
	s_add_i32 s84, s84, 2
	s_add_u32 s36, s36, 0x100
	s_addc_u32 s37, s37, 0
	s_cmp_gt_u32 s84, 41
	s_mov_b64 s[96:97], s[42:43]
	s_cbranch_scc1 .Lpeel_x5
